# six GEMM K-loops: the redundant s_waitcnt lgkmcnt(0) at the head of every MFMA block removed (load segment already drained LDS before its barrier)
# speedup vs baseline: 1.0249x; 1.0006x over previous
; #define PG8_STAGE(bufoff, gbase, voff) do { _Pragma("unroll") for (int _i = 0; _i < 2; ++_i) \
;         __builtin_amdgcn_global_load_lds((const unsigned*)((const char*)(gbase) + (voff)[_i]), (PG8_LAS unsigned*)(lds + (bufoff) + ldsw + _i * 8192), 16, 0, 0); } while (0)
; #define PG8_LDA(dst, b, h) do { _Pragma("unroll") for (int m = 0; m < 4; ++m) _Pragma("unroll") for (int k = 0; k < 2; ++k) dst[m][k] = *(const PG8_LAS bf16x8*)(lds + PG8_SA(b, h) + aoff + m * 2048 + k * 1024); } while (0)
; #define PG8_LDB(dst, b, h) do { _Pragma("unroll") for (int n = 0; n < 2; ++n) _Pragma("unroll") for (int k = 0; k < 2; ++k) dst[n][k] = *(const PG8_LAS bf16x8*)(lds + PG8_SB(b, h) + boff + n * 2048 + k * 1024); } while (0)
; #define PG8_WAIT_V(n) asm volatile("s_waitcnt vmcnt(" #n ")" ::: "memory")
; #define PG8_WAIT_L(n) asm volatile("s_waitcnt lgkmcnt(" #n ")" ::: "memory")
; #define PG8_BAR __builtin_amdgcn_s_barrier()
; #define PG8_SCHED __builtin_amdgcn_sched_barrier(0)
; template <class Epi, class Sched, bool ALIGN_EPI = false, bool SP2 = false>
; __device__ __forceinline__ void gemm_phase(PG8_LAS unsigned char* lds, const Gemm g, const Sched& S, const Epi& E) {
;     ...
;         const char* nA = has_next ? (const char*)g.A + (size_t)nxt.pm * tstep : cA; const char* nB = has_next ? (const char*)g.Bt + (size_t)nxt.pn * tstep : cB;
;         for (int t = 0; t < nt; t += 2) {
;             const bool last = (t == nt - 2);
;             const char* a1 = cA + (size_t)(t + 1) * kstep;
;             const char* a2 = last ? nA : cA + (size_t)(t + 2) * kstep; const char* b2 = last ? nB : cB + (size_t)(t + 2) * kstep;
;             const char* a3 = a2 + kstep; const char* b3 = b2 + kstep;
;             if (last && has_next) S.a_ready(nxt);
;             if constexpr (SP2) {
;             PG8_LDB(B0, 0, 0); PG8_LDB(B1, 0, 1); PG8_SCHED; PG8_LDA(At, 0, 0); PG8_STAGE(PG8_SA(1, 1), a1 + hstep, voffA);
;             PG8_WAIT_V(8); PG8_WAIT_L(0); PG8_BAR; PG8_MMA(0, 0, At, B0); PG8_MMA(0, 1, At, B1); PG8_BAR; PG8_SCHED;
;             PG8_LDA(At, 0, 1); PG8_STAGE(PG8_SB(0, 0), b2, voffB); PG8_STAGE(PG8_SB(0, 1), b2 + hstep, voffB); PG8_STAGE(PG8_SA(0, 0), a2, voffA);
;             PG8_WAIT_V(8); PG8_WAIT_L(0); PG8_BAR; PG8_MMA(1, 0, At, B0); PG8_MMA(1, 1, At, B1); PG8_BAR; PG8_SCHED;
.LBB0_36:
	s_add_u32 s18, s58, 0xffe00080
	s_addc_u32 s19, s59, -1
	s_add_i32 s47, 0, 0x10000
	s_cmpk_eq_i32 s46, 0x7c
	s_cselect_b32 s63, s45, s19
	s_cselect_b32 s62, s73, s18
	v_add_u32_e32 v160, s47, v143
	s_cselect_b32 s19, s37, s79
	s_cselect_b32 s18, s84, s78
	s_add_i32 s80, 0, 0x14000
	ds_read_b128 v[156:159], v160
	ds_read_b128 v[164:167], v160 offset:1024
	ds_read_b128 v[168:171], v160 offset:2048
	ds_read_b128 v[172:175], v160 offset:3072
	v_add_u32_e32 v160, s80, v143
	ds_read_b128 v[176:179], v160
	ds_read_b128 v[180:183], v160 offset:1024
	ds_read_b128 v[184:187], v160 offset:2048
	ds_read_b128 v[204:207], v160 offset:3072
	v_lshl_add_u64 v[160:161], s[58:59], 0, v[152:153]
	s_add_i32 m0, s5, 0xc000
	ds_read_b128 v[208:211], v163
	ds_read_b128 v[212:215], v163 offset:1024
	ds_read_b128 v[216:219], v163 offset:2048
	ds_read_b128 v[220:223], v163 offset:3072
	ds_read_b128 v[224:227], v163 offset:4096
	ds_read_b128 v[228:231], v163 offset:5120
	ds_read_b128 v[232:235], v163 offset:6144
	ds_read_b128 v[236:239], v163 offset:7168
	global_load_lds_dwordx4 v[160:161], off
	v_lshl_add_u64 v[160:161], s[58:59], 0, v[154:155]
	s_add_i32 m0, s5, 0xe000
	s_nop 0
	global_load_lds_dwordx4 v[160:161], off
	s_waitcnt vmcnt(8)
	s_waitcnt lgkmcnt(0)
	s_barrier
	s_setprio 1
	v_mfma_f32_16x16x32_bf16 v[126:129], v[156:159], v[208:211], v[126:129]
	v_mfma_f32_16x16x32_bf16 v[122:125], v[168:171], v[208:211], v[122:125]
	v_mfma_f32_16x16x32_bf16 v[110:113], v[156:159], v[216:219], v[110:113]
	v_mfma_f32_16x16x32_bf16 v[106:109], v[168:171], v[216:219], v[106:109]
	v_mfma_f32_16x16x32_bf16 v[94:97], v[156:159], v[224:227], v[94:97]
	v_mfma_f32_16x16x32_bf16 v[90:93], v[168:171], v[224:227], v[90:93]
	v_mfma_f32_16x16x32_bf16 v[78:81], v[156:159], v[232:235], v[78:81]
	v_mfma_f32_16x16x32_bf16 v[74:77], v[168:171], v[232:235], v[74:77]
	s_setprio 0
	s_setprio 1
	v_mfma_f32_16x16x32_bf16 v[126:129], v[164:167], v[212:215], v[126:129]
	v_mfma_f32_16x16x32_bf16 v[122:125], v[172:175], v[212:215], v[122:125]
	v_mfma_f32_16x16x32_bf16 v[110:113], v[164:167], v[220:223], v[110:113]
	v_mfma_f32_16x16x32_bf16 v[106:109], v[172:175], v[220:223], v[106:109]
	v_mfma_f32_16x16x32_bf16 v[94:97], v[164:167], v[228:231], v[94:97]
	v_mfma_f32_16x16x32_bf16 v[90:93], v[172:175], v[228:231], v[90:93]
	v_mfma_f32_16x16x32_bf16 v[78:81], v[164:167], v[236:239], v[78:81]
	v_mfma_f32_16x16x32_bf16 v[74:77], v[172:175], v[236:239], v[74:77]
	s_setprio 0
	s_setprio 1
	v_mfma_f32_16x16x32_bf16 v[118:121], v[176:179], v[208:211], v[118:121]
	v_mfma_f32_16x16x32_bf16 v[114:117], v[184:187], v[208:211], v[114:117]
	v_mfma_f32_16x16x32_bf16 v[102:105], v[176:179], v[216:219], v[102:105]
	v_mfma_f32_16x16x32_bf16 v[98:101], v[184:187], v[216:219], v[98:101]
	v_mfma_f32_16x16x32_bf16 v[86:89], v[176:179], v[224:227], v[86:89]
	v_mfma_f32_16x16x32_bf16 v[82:85], v[184:187], v[224:227], v[82:85]
	v_mfma_f32_16x16x32_bf16 v[70:73], v[176:179], v[232:235], v[70:73]
	v_mfma_f32_16x16x32_bf16 v[66:69], v[184:187], v[232:235], v[66:69]
	s_setprio 0
	s_setprio 1
	v_mfma_f32_16x16x32_bf16 v[118:121], v[180:183], v[212:215], v[118:121]
	v_mfma_f32_16x16x32_bf16 v[114:117], v[204:207], v[212:215], v[114:117]
	v_mfma_f32_16x16x32_bf16 v[102:105], v[180:183], v[220:223], v[102:105]
	v_mfma_f32_16x16x32_bf16 v[98:101], v[204:207], v[220:223], v[98:101]
	v_mfma_f32_16x16x32_bf16 v[86:89], v[180:183], v[228:231], v[86:89]
	v_mfma_f32_16x16x32_bf16 v[82:85], v[204:207], v[228:231], v[82:85]
	v_mfma_f32_16x16x32_bf16 v[70:73], v[180:183], v[236:239], v[70:73]
	v_mfma_f32_16x16x32_bf16 v[66:69], v[204:207], v[236:239], v[66:69]
	s_setprio 0
	s_barrier
	s_add_i32 s47, s47, s4
	v_lshl_add_u64 v[160:161], s[18:19], 0, v[148:149]
	s_mov_b32 m0, s47
	ds_read_b128 v[208:211], v163 offset:16384
	ds_read_b128 v[212:215], v163 offset:17408
	ds_read_b128 v[216:219], v163 offset:18432
	ds_read_b128 v[220:223], v163 offset:19456
	ds_read_b128 v[224:227], v163 offset:20480
	ds_read_b128 v[228:231], v163 offset:21504
	ds_read_b128 v[232:235], v163 offset:22528
	ds_read_b128 v[236:239], v163 offset:23552
	global_load_lds_dwordx4 v[160:161], off
	s_add_i32 m0, s47, 0x2000
	s_add_u32 s76, s18, 0x200000
	v_lshl_add_u64 v[240:241], s[18:19], 0, v[144:145]
	s_addc_u32 s77, s19, 0
	s_add_i32 s47, s80, s4
	global_load_lds_dwordx4 v[240:241], off
	v_lshl_add_u64 v[242:243], s[76:77], 0, v[148:149]
	s_mov_b32 m0, s47
	v_lshl_add_u64 v[244:245], s[62:63], 0, v[146:147]
	global_load_lds_dwordx4 v[242:243], off
	v_lshl_add_u64 v[242:243], s[76:77], 0, v[144:145]
	s_add_i32 m0, s47, 0x2000
	s_nop 0
	global_load_lds_dwordx4 v[242:243], off
	v_lshl_add_u64 v[242:243], s[62:63], 0, v[150:151]
	s_mov_b32 m0, s5
	s_nop 0
	global_load_lds_dwordx4 v[242:243], off
	s_mov_b32 m0, s30
	s_nop 0
	global_load_lds_dwordx4 v[244:245], off
	s_waitcnt vmcnt(8)
	s_waitcnt lgkmcnt(0)
	s_barrier
; #define PG8_STAGE(bufoff, gbase, voff) do { _Pragma("unroll") for (int _i = 0; _i < 2; ++_i) \
;         __builtin_amdgcn_global_load_lds((const unsigned*)((const char*)(gbase) + (voff)[_i]), (PG8_LAS unsigned*)(lds + (bufoff) + ldsw + _i * 8192), 16, 0, 0); } while (0)
; #define PG8_LDA(dst, b, h) do { _Pragma("unroll") for (int m = 0; m < 4; ++m) _Pragma("unroll") for (int k = 0; k < 2; ++k) dst[m][k] = *(const PG8_LAS bf16x8*)(lds + PG8_SA(b, h) + aoff + m * 2048 + k * 1024); } while (0)
; #define PG8_LDB(dst, b, h) do { _Pragma("unroll") for (int n = 0; n < 2; ++n) _Pragma("unroll") for (int k = 0; k < 2; ++k) dst[n][k] = *(const PG8_LAS bf16x8*)(lds + PG8_SB(b, h) + boff + n * 2048 + k * 1024); } while (0)
; #define PG8_MMA(ai, bj, At, Bt) do { __builtin_amdgcn_s_setprio(1); _Pragma("unroll") for (int m = 0; m < 4; ++m) _Pragma("unroll") for (int n = 0; n < 2; ++n) _Pragma("unroll") for (int k = 0; k < 2; ++k) \
;         acc[ai][bj][m][n] = __builtin_amdgcn_mfma_f32_16x16x32_bf16(Bt[n][k], At[m][k], acc[ai][bj][m][n], 0, 0, 0); __builtin_amdgcn_s_setprio(0); } while (0)
; #define PG8_WAIT_V(n) asm volatile("s_waitcnt vmcnt(" #n ")" ::: "memory")
; #define PG8_WAIT_L(n) asm volatile("s_waitcnt lgkmcnt(" #n ")" ::: "memory")
; #define PG8_BAR __builtin_amdgcn_s_barrier()
; #define PG8_SCHED __builtin_amdgcn_sched_barrier(0)
; template <class Epi, class Sched, bool ALIGN_EPI = false, bool SP2 = false>
; __device__ __forceinline__ void gemm_phase(PG8_LAS unsigned char* lds, const Gemm g, const Sched& S, const Epi& E) {
;     ...
;             PG8_WAIT_V(8); PG8_WAIT_L(0); PG8_BAR; PG8_MMA(1, 0, At, B0); PG8_MMA(1, 1, At, B1); PG8_BAR; PG8_SCHED;
;             PG8_LDB(B0, 1, 0); PG8_LDB(B1, 1, 1); PG8_SCHED; PG8_LDA(At, 1, 0); PG8_STAGE(PG8_SA(0, 1), a2 + hstep, voffA);
;             PG8_WAIT_V(8); PG8_WAIT_L(0); PG8_BAR; PG8_MMA(0, 0, At, B0); PG8_MMA(0, 1, At, B1); PG8_BAR; PG8_SCHED;
	s_setprio 1
	v_mfma_f32_16x16x32_bf16 v[62:65], v[156:159], v[208:211], v[62:65]
	v_mfma_f32_16x16x32_bf16 v[58:61], v[168:171], v[208:211], v[58:61]
	v_mfma_f32_16x16x32_bf16 v[46:49], v[156:159], v[216:219], v[46:49]
	v_mfma_f32_16x16x32_bf16 v[42:45], v[168:171], v[216:219], v[42:45]
	v_mfma_f32_16x16x32_bf16 v[30:33], v[156:159], v[224:227], v[30:33]
	v_mfma_f32_16x16x32_bf16 v[26:29], v[168:171], v[224:227], v[26:29]
	v_mfma_f32_16x16x32_bf16 v[14:17], v[156:159], v[232:235], v[14:17]
	v_mfma_f32_16x16x32_bf16 v[10:13], v[168:171], v[232:235], v[10:13]
	s_setprio 0
	s_setprio 1
	v_mfma_f32_16x16x32_bf16 v[62:65], v[164:167], v[212:215], v[62:65]
	v_mfma_f32_16x16x32_bf16 v[58:61], v[172:175], v[212:215], v[58:61]
	v_mfma_f32_16x16x32_bf16 v[46:49], v[164:167], v[220:223], v[46:49]
	v_mfma_f32_16x16x32_bf16 v[42:45], v[172:175], v[220:223], v[42:45]
	v_mfma_f32_16x16x32_bf16 v[30:33], v[164:167], v[228:231], v[30:33]
	v_mfma_f32_16x16x32_bf16 v[26:29], v[172:175], v[228:231], v[26:29]
	v_mfma_f32_16x16x32_bf16 v[14:17], v[164:167], v[236:239], v[14:17]
	v_mfma_f32_16x16x32_bf16 v[10:13], v[172:175], v[236:239], v[10:13]
	s_setprio 0
	s_setprio 1
	v_mfma_f32_16x16x32_bf16 v[54:57], v[176:179], v[208:211], v[54:57]
	v_mfma_f32_16x16x32_bf16 v[50:53], v[184:187], v[208:211], v[50:53]
	v_mfma_f32_16x16x32_bf16 v[38:41], v[176:179], v[216:219], v[38:41]
	v_mfma_f32_16x16x32_bf16 v[34:37], v[184:187], v[216:219], v[34:37]
	v_mfma_f32_16x16x32_bf16 v[22:25], v[176:179], v[224:227], v[22:25]
	v_mfma_f32_16x16x32_bf16 v[18:21], v[184:187], v[224:227], v[18:21]
	v_mfma_f32_16x16x32_bf16 v[6:9], v[176:179], v[232:235], v[6:9]
	v_mfma_f32_16x16x32_bf16 v[2:5], v[184:187], v[232:235], v[2:5]
	s_setprio 0
	s_setprio 1
	v_mfma_f32_16x16x32_bf16 v[54:57], v[180:183], v[212:215], v[54:57]
	v_mfma_f32_16x16x32_bf16 v[50:53], v[204:207], v[212:215], v[50:53]
	v_mfma_f32_16x16x32_bf16 v[38:41], v[180:183], v[220:223], v[38:41]
	v_mfma_f32_16x16x32_bf16 v[34:37], v[204:207], v[220:223], v[34:37]
	v_mfma_f32_16x16x32_bf16 v[22:25], v[180:183], v[228:231], v[22:25]
	v_mfma_f32_16x16x32_bf16 v[18:21], v[204:207], v[228:231], v[18:21]
	v_mfma_f32_16x16x32_bf16 v[6:9], v[180:183], v[236:239], v[6:9]
	v_mfma_f32_16x16x32_bf16 v[2:5], v[204:207], v[236:239], v[2:5]
	s_setprio 0
	s_barrier
	s_add_i32 s47, 0, 0x18000
	s_add_i32 s76, 0, 0x1c000
	v_add_u32_e32 v172, s47, v143
	v_add_u32_e32 v203, s76, v143
	ds_read_b128 v[156:159], v172
	ds_read_b128 v[164:167], v172 offset:1024
	ds_read_b128 v[168:171], v172 offset:2048
	ds_read_b128 v[172:175], v172 offset:3072
	ds_read_b128 v[176:179], v203
	ds_read_b128 v[180:183], v203 offset:1024
	ds_read_b128 v[184:187], v203 offset:2048
	ds_read_b128 v[204:207], v203 offset:3072
	s_add_u32 s62, s62, 0x200000
	s_addc_u32 s63, s63, 0
	s_mov_b32 m0, s57
	v_lshl_add_u64 v[246:247], s[62:63], 0, v[150:151]
	ds_read_b128 v[208:211], v163 offset:32768
	ds_read_b128 v[212:215], v163 offset:33792
	ds_read_b128 v[216:219], v163 offset:34816
	ds_read_b128 v[220:223], v163 offset:35840
	ds_read_b128 v[224:227], v163 offset:36864
	ds_read_b128 v[228:231], v163 offset:37888
	ds_read_b128 v[232:235], v163 offset:38912
	ds_read_b128 v[236:239], v163 offset:39936
	global_load_lds_dwordx4 v[246:247], off
	v_lshl_add_u64 v[246:247], s[62:63], 0, v[146:147]
	s_mov_b32 m0, s67
	s_nop 0
	global_load_lds_dwordx4 v[246:247], off
	s_waitcnt vmcnt(8)
	s_waitcnt lgkmcnt(0)
	s_barrier
	s_setprio 1
	v_mfma_f32_16x16x32_bf16 v[126:129], v[156:159], v[208:211], v[126:129]
	v_mfma_f32_16x16x32_bf16 v[122:125], v[168:171], v[208:211], v[122:125]
	v_mfma_f32_16x16x32_bf16 v[110:113], v[156:159], v[216:219], v[110:113]
	v_mfma_f32_16x16x32_bf16 v[106:109], v[168:171], v[216:219], v[106:109]
	v_mfma_f32_16x16x32_bf16 v[94:97], v[156:159], v[224:227], v[94:97]
	v_mfma_f32_16x16x32_bf16 v[90:93], v[168:171], v[224:227], v[90:93]
	v_mfma_f32_16x16x32_bf16 v[78:81], v[156:159], v[232:235], v[78:81]
	v_mfma_f32_16x16x32_bf16 v[74:77], v[168:171], v[232:235], v[74:77]
	s_setprio 0
	s_setprio 1
	v_mfma_f32_16x16x32_bf16 v[126:129], v[164:167], v[212:215], v[126:129]
	v_mfma_f32_16x16x32_bf16 v[122:125], v[172:175], v[212:215], v[122:125]
	v_mfma_f32_16x16x32_bf16 v[110:113], v[164:167], v[220:223], v[110:113]
	v_mfma_f32_16x16x32_bf16 v[106:109], v[172:175], v[220:223], v[106:109]
	v_mfma_f32_16x16x32_bf16 v[94:97], v[164:167], v[228:231], v[94:97]
	v_mfma_f32_16x16x32_bf16 v[90:93], v[172:175], v[228:231], v[90:93]
	v_mfma_f32_16x16x32_bf16 v[78:81], v[164:167], v[236:239], v[78:81]
	v_mfma_f32_16x16x32_bf16 v[74:77], v[172:175], v[236:239], v[74:77]
	s_setprio 0
	s_setprio 1
	v_mfma_f32_16x16x32_bf16 v[118:121], v[176:179], v[208:211], v[118:121]
	v_mfma_f32_16x16x32_bf16 v[114:117], v[184:187], v[208:211], v[114:117]
	v_mfma_f32_16x16x32_bf16 v[102:105], v[176:179], v[216:219], v[102:105]
	v_mfma_f32_16x16x32_bf16 v[98:101], v[184:187], v[216:219], v[98:101]
	v_mfma_f32_16x16x32_bf16 v[86:89], v[176:179], v[224:227], v[86:89]
	v_mfma_f32_16x16x32_bf16 v[82:85], v[184:187], v[224:227], v[82:85]
	v_mfma_f32_16x16x32_bf16 v[70:73], v[176:179], v[232:235], v[70:73]
	v_mfma_f32_16x16x32_bf16 v[66:69], v[184:187], v[232:235], v[66:69]
	s_setprio 0
	s_setprio 1
	v_mfma_f32_16x16x32_bf16 v[118:121], v[180:183], v[212:215], v[118:121]
	v_mfma_f32_16x16x32_bf16 v[114:117], v[204:207], v[212:215], v[114:117]
	v_mfma_f32_16x16x32_bf16 v[102:105], v[180:183], v[220:223], v[102:105]
	v_mfma_f32_16x16x32_bf16 v[98:101], v[204:207], v[220:223], v[98:101]
	v_mfma_f32_16x16x32_bf16 v[86:89], v[180:183], v[228:231], v[86:89]
	v_mfma_f32_16x16x32_bf16 v[82:85], v[204:207], v[228:231], v[82:85]
	v_mfma_f32_16x16x32_bf16 v[70:73], v[180:183], v[236:239], v[70:73]
	v_mfma_f32_16x16x32_bf16 v[66:69], v[204:207], v[236:239], v[66:69]
	s_setprio 0
	s_barrier
; #define PG8_STAGE(bufoff, gbase, voff) do { _Pragma("unroll") for (int _i = 0; _i < 2; ++_i) \
;         __builtin_amdgcn_global_load_lds((const unsigned*)((const char*)(gbase) + (voff)[_i]), (PG8_LAS unsigned*)(lds + (bufoff) + ldsw + _i * 8192), 16, 0, 0); } while (0)
; #define PG8_LDA(dst, b, h) do { _Pragma("unroll") for (int m = 0; m < 4; ++m) _Pragma("unroll") for (int k = 0; k < 2; ++k) dst[m][k] = *(const PG8_LAS bf16x8*)(lds + PG8_SA(b, h) + aoff + m * 2048 + k * 1024); } while (0)
; #define PG8_MMA(ai, bj, At, Bt) do { __builtin_amdgcn_s_setprio(1); _Pragma("unroll") for (int m = 0; m < 4; ++m) _Pragma("unroll") for (int n = 0; n < 2; ++n) _Pragma("unroll") for (int k = 0; k < 2; ++k) \
;         acc[ai][bj][m][n] = __builtin_amdgcn_mfma_f32_16x16x32_bf16(Bt[n][k], At[m][k], acc[ai][bj][m][n], 0, 0, 0); __builtin_amdgcn_s_setprio(0); } while (0)
; #define PG8_WAIT_V(n) asm volatile("s_waitcnt vmcnt(" #n ")" ::: "memory")
; #define PG8_WAIT_L(n) asm volatile("s_waitcnt lgkmcnt(" #n ")" ::: "memory")
; #define PG8_BAR __builtin_amdgcn_s_barrier()
; #define PG8_SCHED __builtin_amdgcn_sched_barrier(0)
; template <class Epi, class Sched, bool ALIGN_EPI = false, bool SP2 = false>
; __device__ __forceinline__ void gemm_phase(PG8_LAS unsigned char* lds, const Gemm g, const Sched& S, const Epi& E) {
;     ...
;             PG8_LDA(At, 1, 1); PG8_STAGE(PG8_SB(1, 0), b3, voffB); PG8_STAGE(PG8_SB(1, 1), b3 + hstep, voffB); PG8_STAGE(PG8_SA(1, 0), a3, voffA);
;             PG8_WAIT_V(8); PG8_WAIT_L(0); PG8_BAR; PG8_MMA(1, 0, At, B0); PG8_MMA(1, 1, At, B1); PG8_BAR; PG8_SCHED;
;     ...
;         if constexpr (ALIGN_EPI) { if (wr == 0) PG8_BAR; }
	s_add_i32 s47, s47, s4
	v_lshl_add_u64 v[160:161], v[160:161], 0, s[68:69]
	s_mov_b32 m0, s47
	ds_read_b128 v[208:211], v163 offset:49152
	ds_read_b128 v[212:215], v163 offset:50176
	ds_read_b128 v[216:219], v163 offset:51200
	ds_read_b128 v[220:223], v163 offset:52224
	ds_read_b128 v[224:227], v163 offset:53248
	ds_read_b128 v[228:231], v163 offset:54272
	ds_read_b128 v[232:235], v163 offset:55296
	ds_read_b128 v[236:239], v163 offset:56320
	global_load_lds_dwordx4 v[160:161], off
	s_add_i32 m0, s47, 0x2000
	s_add_u32 s18, s18, 0x200080
	v_lshl_add_u64 v[160:161], v[240:241], 0, s[68:69]
	s_addc_u32 s19, s19, 0
	s_add_i32 s47, s76, s4
	global_load_lds_dwordx4 v[160:161], off
	v_lshl_add_u64 v[160:161], s[18:19], 0, v[148:149]
	s_mov_b32 m0, s47
	s_nop 0
	global_load_lds_dwordx4 v[160:161], off
	v_lshl_add_u64 v[160:161], s[18:19], 0, v[144:145]
	s_add_i32 m0, s47, 0x2000
	s_nop 0
	global_load_lds_dwordx4 v[160:161], off
	v_lshl_add_u64 v[160:161], v[242:243], 0, s[68:69]
	s_mov_b32 m0, s1
	s_nop 0
	global_load_lds_dwordx4 v[160:161], off
	v_lshl_add_u64 v[160:161], v[244:245], 0, s[68:69]
	s_mov_b32 m0, s60
	s_nop 0
	global_load_lds_dwordx4 v[160:161], off
	s_waitcnt vmcnt(8)
	s_waitcnt lgkmcnt(0)
	s_barrier
	s_setprio 1
	v_mfma_f32_16x16x32_bf16 v[62:65], v[156:159], v[208:211], v[62:65]
	v_mfma_f32_16x16x32_bf16 v[58:61], v[168:171], v[208:211], v[58:61]
	v_mfma_f32_16x16x32_bf16 v[46:49], v[156:159], v[216:219], v[46:49]
	v_mfma_f32_16x16x32_bf16 v[42:45], v[168:171], v[216:219], v[42:45]
	v_mfma_f32_16x16x32_bf16 v[30:33], v[156:159], v[224:227], v[30:33]
	v_mfma_f32_16x16x32_bf16 v[26:29], v[168:171], v[224:227], v[26:29]
	v_mfma_f32_16x16x32_bf16 v[14:17], v[156:159], v[232:235], v[14:17]
	v_mfma_f32_16x16x32_bf16 v[10:13], v[168:171], v[232:235], v[10:13]
	s_setprio 0
	s_setprio 1
	v_mfma_f32_16x16x32_bf16 v[62:65], v[164:167], v[212:215], v[62:65]
	v_mfma_f32_16x16x32_bf16 v[58:61], v[172:175], v[212:215], v[58:61]
	v_mfma_f32_16x16x32_bf16 v[46:49], v[164:167], v[220:223], v[46:49]
	v_mfma_f32_16x16x32_bf16 v[42:45], v[172:175], v[220:223], v[42:45]
	v_mfma_f32_16x16x32_bf16 v[30:33], v[164:167], v[228:231], v[30:33]
	v_mfma_f32_16x16x32_bf16 v[26:29], v[172:175], v[228:231], v[26:29]
	v_mfma_f32_16x16x32_bf16 v[14:17], v[164:167], v[236:239], v[14:17]
	v_mfma_f32_16x16x32_bf16 v[10:13], v[172:175], v[236:239], v[10:13]
	s_setprio 0
	s_setprio 1
	v_mfma_f32_16x16x32_bf16 v[54:57], v[176:179], v[208:211], v[54:57]
	v_mfma_f32_16x16x32_bf16 v[50:53], v[184:187], v[208:211], v[50:53]
	v_mfma_f32_16x16x32_bf16 v[38:41], v[176:179], v[216:219], v[38:41]
	v_mfma_f32_16x16x32_bf16 v[34:37], v[184:187], v[216:219], v[34:37]
	v_mfma_f32_16x16x32_bf16 v[22:25], v[176:179], v[224:227], v[22:25]
	v_mfma_f32_16x16x32_bf16 v[18:21], v[184:187], v[224:227], v[18:21]
	v_mfma_f32_16x16x32_bf16 v[6:9], v[176:179], v[232:235], v[6:9]
	v_mfma_f32_16x16x32_bf16 v[2:5], v[184:187], v[232:235], v[2:5]
	s_setprio 0
	s_setprio 1
	v_mfma_f32_16x16x32_bf16 v[54:57], v[180:183], v[212:215], v[54:57]
	v_mfma_f32_16x16x32_bf16 v[50:53], v[204:207], v[212:215], v[50:53]
	v_mfma_f32_16x16x32_bf16 v[38:41], v[180:183], v[220:223], v[38:41]
	v_mfma_f32_16x16x32_bf16 v[34:37], v[204:207], v[220:223], v[34:37]
	v_mfma_f32_16x16x32_bf16 v[22:25], v[180:183], v[228:231], v[22:25]
	v_mfma_f32_16x16x32_bf16 v[18:21], v[204:207], v[228:231], v[18:21]
	v_mfma_f32_16x16x32_bf16 v[6:9], v[180:183], v[236:239], v[6:9]
	v_mfma_f32_16x16x32_bf16 v[2:5], v[204:207], v[236:239], v[2:5]
	s_setprio 0
	s_barrier
	s_add_i32 s46, s46, 2
	s_add_u32 s58, s58, 0x100
	s_addc_u32 s59, s59, 0
	s_add_u32 s78, s78, 0x100
	s_addc_u32 s79, s79, 0
	s_cmpk_gt_u32 s46, 0x7d
	s_cbranch_scc0 .LBB0_36
	s_and_b64 vcc, exec, s[12:13]
	s_cbranch_vccz .LBB0_39
	s_barrier

; #define PG8_STAGE(bufoff, gbase, voff) do { _Pragma("unroll") for (int _i = 0; _i < 2; ++_i) \
;         __builtin_amdgcn_global_load_lds((const unsigned*)((const char*)(gbase) + (voff)[_i]), (PG8_LAS unsigned*)(lds + (bufoff) + ldsw + _i * 8192), 16, 0, 0); } while (0)
; #define PG8_LDA(dst, b, h) do { _Pragma("unroll") for (int m = 0; m < 4; ++m) _Pragma("unroll") for (int k = 0; k < 2; ++k) dst[m][k] = *(const PG8_LAS bf16x8*)(lds + PG8_SA(b, h) + aoff + m * 2048 + k * 1024); } while (0)
; #define PG8_LDB(dst, b, h) do { _Pragma("unroll") for (int n = 0; n < 2; ++n) _Pragma("unroll") for (int k = 0; k < 2; ++k) dst[n][k] = *(const PG8_LAS bf16x8*)(lds + PG8_SB(b, h) + boff + n * 2048 + k * 1024); } while (0)
; #define PG8_WAIT_V(n) asm volatile("s_waitcnt vmcnt(" #n ")" ::: "memory")
; #define PG8_WAIT_L(n) asm volatile("s_waitcnt lgkmcnt(" #n ")" ::: "memory")
; #define PG8_BAR __builtin_amdgcn_s_barrier()
; #define PG8_SCHED __builtin_amdgcn_sched_barrier(0)
; template <class Epi, class Sched, bool ALIGN_EPI = false, bool SP2 = false>
; __device__ __forceinline__ void gemm_phase(PG8_LAS unsigned char* lds, const Gemm g, const Sched& S, const Epi& E) {
;     ...
;         const char* nA = has_next ? (const char*)g.A + (size_t)nxt.pm * tstep : cA; const char* nB = has_next ? (const char*)g.Bt + (size_t)nxt.pn * tstep : cB;
;         for (int t = 0; t < nt; t += 2) {
;             const bool last = (t == nt - 2);
;             const char* a1 = cA + (size_t)(t + 1) * kstep;
;             const char* a2 = last ? nA : cA + (size_t)(t + 2) * kstep; const char* b2 = last ? nB : cB + (size_t)(t + 2) * kstep;
;             const char* a3 = a2 + kstep; const char* b3 = b2 + kstep;
;             if (last && has_next) S.a_ready(nxt);
;             if constexpr (SP2) {
;             PG8_LDB(B0, 0, 0); PG8_LDB(B1, 0, 1); PG8_SCHED; PG8_LDA(At, 0, 0); PG8_STAGE(PG8_SA(1, 1), a1 + hstep, voffA);
;             PG8_WAIT_V(8); PG8_WAIT_L(0); PG8_BAR; PG8_MMA(0, 0, At, B0); PG8_MMA(0, 1, At, B1); PG8_BAR; PG8_SCHED;
;             PG8_LDA(At, 0, 1); PG8_STAGE(PG8_SB(0, 0), b2, voffB); PG8_STAGE(PG8_SB(0, 1), b2 + hstep, voffB); PG8_STAGE(PG8_SA(0, 0), a2, voffA);
;             PG8_WAIT_V(8); PG8_WAIT_L(0); PG8_BAR; PG8_MMA(1, 0, At, B0); PG8_MMA(1, 1, At, B1); PG8_BAR; PG8_SCHED;
.LBB0_76:
	s_add_u32 s18, s0, 0xfff80080
	s_addc_u32 s19, s1, -1
	s_add_i32 s47, 0, 0x10000
	s_cmp_eq_u32 s46, 28
	s_cselect_b32 s59, s60, s19
	s_cselect_b32 s58, s73, s18
	v_add_u32_e32 v158, s47, v143
	s_cselect_b32 s19, s45, s79
	s_cselect_b32 s18, s84, s78
	s_add_i32 s80, 0, 0x14000
	ds_read_b128 v[162:165], v158
	ds_read_b128 v[166:169], v158 offset:1024
	ds_read_b128 v[170:173], v158 offset:2048
	ds_read_b128 v[174:177], v158 offset:3072
	v_add_u32_e32 v158, s80, v143
	ds_read_b128 v[178:181], v158
	ds_read_b128 v[182:185], v158 offset:1024
	ds_read_b128 v[204:207], v158 offset:2048
	ds_read_b128 v[208:211], v158 offset:3072
	v_lshl_add_u64 v[158:159], s[0:1], 0, v[154:155]
	s_add_i32 m0, s62, 0xc000
	ds_read_b128 v[212:215], v161
	ds_read_b128 v[216:219], v161 offset:1024
	ds_read_b128 v[220:223], v161 offset:2048
	ds_read_b128 v[224:227], v161 offset:3072
	ds_read_b128 v[228:231], v161 offset:4096
	ds_read_b128 v[232:235], v161 offset:5120
	ds_read_b128 v[236:239], v161 offset:6144
	ds_read_b128 v[240:243], v161 offset:7168
	global_load_lds_dwordx4 v[158:159], off
	v_lshl_add_u64 v[158:159], s[0:1], 0, v[156:157]
	s_add_i32 m0, s62, 0xe000
	s_nop 0
	global_load_lds_dwordx4 v[158:159], off
	s_waitcnt vmcnt(8)
	s_waitcnt lgkmcnt(0)
	s_barrier
	s_setprio 1
	v_mfma_f32_16x16x32_bf16 v[126:129], v[162:165], v[212:215], v[126:129]
	v_mfma_f32_16x16x32_bf16 v[122:125], v[170:173], v[212:215], v[122:125]
	v_mfma_f32_16x16x32_bf16 v[110:113], v[162:165], v[220:223], v[110:113]
	v_mfma_f32_16x16x32_bf16 v[106:109], v[170:173], v[220:223], v[106:109]
	v_mfma_f32_16x16x32_bf16 v[94:97], v[162:165], v[228:231], v[94:97]
	v_mfma_f32_16x16x32_bf16 v[90:93], v[170:173], v[228:231], v[90:93]
	v_mfma_f32_16x16x32_bf16 v[78:81], v[162:165], v[236:239], v[78:81]
	v_mfma_f32_16x16x32_bf16 v[74:77], v[170:173], v[236:239], v[74:77]
	s_setprio 0
	s_setprio 1
	v_mfma_f32_16x16x32_bf16 v[126:129], v[166:169], v[216:219], v[126:129]
	v_mfma_f32_16x16x32_bf16 v[122:125], v[174:177], v[216:219], v[122:125]
	v_mfma_f32_16x16x32_bf16 v[110:113], v[166:169], v[224:227], v[110:113]
	v_mfma_f32_16x16x32_bf16 v[106:109], v[174:177], v[224:227], v[106:109]
	v_mfma_f32_16x16x32_bf16 v[94:97], v[166:169], v[232:235], v[94:97]
	v_mfma_f32_16x16x32_bf16 v[90:93], v[174:177], v[232:235], v[90:93]
	v_mfma_f32_16x16x32_bf16 v[78:81], v[166:169], v[240:243], v[78:81]
	v_mfma_f32_16x16x32_bf16 v[74:77], v[174:177], v[240:243], v[74:77]
	s_setprio 0
	s_setprio 1
	v_mfma_f32_16x16x32_bf16 v[118:121], v[178:181], v[212:215], v[118:121]
	v_mfma_f32_16x16x32_bf16 v[114:117], v[204:207], v[212:215], v[114:117]
	v_mfma_f32_16x16x32_bf16 v[102:105], v[178:181], v[220:223], v[102:105]
	v_mfma_f32_16x16x32_bf16 v[98:101], v[204:207], v[220:223], v[98:101]
	v_mfma_f32_16x16x32_bf16 v[86:89], v[178:181], v[228:231], v[86:89]
	v_mfma_f32_16x16x32_bf16 v[82:85], v[204:207], v[228:231], v[82:85]
	v_mfma_f32_16x16x32_bf16 v[70:73], v[178:181], v[236:239], v[70:73]
	v_mfma_f32_16x16x32_bf16 v[66:69], v[204:207], v[236:239], v[66:69]
	s_setprio 0
	s_setprio 1
	v_mfma_f32_16x16x32_bf16 v[118:121], v[182:185], v[216:219], v[118:121]
	v_mfma_f32_16x16x32_bf16 v[114:117], v[208:211], v[216:219], v[114:117]
	v_mfma_f32_16x16x32_bf16 v[102:105], v[182:185], v[224:227], v[102:105]
	v_mfma_f32_16x16x32_bf16 v[98:101], v[208:211], v[224:227], v[98:101]
	v_mfma_f32_16x16x32_bf16 v[86:89], v[182:185], v[232:235], v[86:89]
	v_mfma_f32_16x16x32_bf16 v[82:85], v[208:211], v[232:235], v[82:85]
	v_mfma_f32_16x16x32_bf16 v[70:73], v[182:185], v[240:243], v[70:73]
	v_mfma_f32_16x16x32_bf16 v[66:69], v[208:211], v[240:243], v[66:69]
	s_setprio 0
	s_barrier
	s_add_i32 s47, s47, s54
	v_lshl_add_u64 v[158:159], s[18:19], 0, v[148:149]
	s_mov_b32 m0, s47
	ds_read_b128 v[212:215], v161 offset:16384
	ds_read_b128 v[216:219], v161 offset:17408
	ds_read_b128 v[220:223], v161 offset:18432
	ds_read_b128 v[224:227], v161 offset:19456
	ds_read_b128 v[228:231], v161 offset:20480
	ds_read_b128 v[232:235], v161 offset:21504
	ds_read_b128 v[236:239], v161 offset:22528
	ds_read_b128 v[240:243], v161 offset:23552
	global_load_lds_dwordx4 v[158:159], off
	s_add_i32 m0, s47, 0x2000
	s_add_u32 s76, s18, 0x80000
	v_lshl_add_u64 v[186:187], s[18:19], 0, v[144:145]
	s_addc_u32 s77, s19, 0
	s_add_i32 s47, s80, s54
	global_load_lds_dwordx4 v[186:187], off
	v_lshl_add_u64 v[244:245], s[76:77], 0, v[148:149]
	s_mov_b32 m0, s47
	v_lshl_add_u64 v[246:247], s[58:59], 0, v[146:147]
	global_load_lds_dwordx4 v[244:245], off
	v_lshl_add_u64 v[244:245], s[76:77], 0, v[144:145]
	s_add_i32 m0, s47, 0x2000
	s_nop 0
	global_load_lds_dwordx4 v[244:245], off
	v_lshl_add_u64 v[244:245], s[58:59], 0, v[150:151]
	s_mov_b32 m0, s62
	s_nop 0
	global_load_lds_dwordx4 v[244:245], off
	s_mov_b32 m0, s63
	s_nop 0
	global_load_lds_dwordx4 v[246:247], off
	s_waitcnt vmcnt(8)
	s_waitcnt lgkmcnt(0)
	s_barrier
; #define PG8_STAGE(bufoff, gbase, voff) do { _Pragma("unroll") for (int _i = 0; _i < 2; ++_i) \
;         __builtin_amdgcn_global_load_lds((const unsigned*)((const char*)(gbase) + (voff)[_i]), (PG8_LAS unsigned*)(lds + (bufoff) + ldsw + _i * 8192), 16, 0, 0); } while (0)
; #define PG8_LDA(dst, b, h) do { _Pragma("unroll") for (int m = 0; m < 4; ++m) _Pragma("unroll") for (int k = 0; k < 2; ++k) dst[m][k] = *(const PG8_LAS bf16x8*)(lds + PG8_SA(b, h) + aoff + m * 2048 + k * 1024); } while (0)
; #define PG8_LDB(dst, b, h) do { _Pragma("unroll") for (int n = 0; n < 2; ++n) _Pragma("unroll") for (int k = 0; k < 2; ++k) dst[n][k] = *(const PG8_LAS bf16x8*)(lds + PG8_SB(b, h) + boff + n * 2048 + k * 1024); } while (0)
; #define PG8_MMA(ai, bj, At, Bt) do { __builtin_amdgcn_s_setprio(1); _Pragma("unroll") for (int m = 0; m < 4; ++m) _Pragma("unroll") for (int n = 0; n < 2; ++n) _Pragma("unroll") for (int k = 0; k < 2; ++k) \
;         acc[ai][bj][m][n] = __builtin_amdgcn_mfma_f32_16x16x32_bf16(Bt[n][k], At[m][k], acc[ai][bj][m][n], 0, 0, 0); __builtin_amdgcn_s_setprio(0); } while (0)
; #define PG8_WAIT_V(n) asm volatile("s_waitcnt vmcnt(" #n ")" ::: "memory")
; #define PG8_WAIT_L(n) asm volatile("s_waitcnt lgkmcnt(" #n ")" ::: "memory")
; #define PG8_BAR __builtin_amdgcn_s_barrier()
; #define PG8_SCHED __builtin_amdgcn_sched_barrier(0)
; template <class Epi, class Sched, bool ALIGN_EPI = false, bool SP2 = false>
; __device__ __forceinline__ void gemm_phase(PG8_LAS unsigned char* lds, const Gemm g, const Sched& S, const Epi& E) {
;     ...
;             PG8_WAIT_V(8); PG8_WAIT_L(0); PG8_BAR; PG8_MMA(1, 0, At, B0); PG8_MMA(1, 1, At, B1); PG8_BAR; PG8_SCHED;
;             PG8_LDB(B0, 1, 0); PG8_LDB(B1, 1, 1); PG8_SCHED; PG8_LDA(At, 1, 0); PG8_STAGE(PG8_SA(0, 1), a2 + hstep, voffA);
;             PG8_WAIT_V(8); PG8_WAIT_L(0); PG8_BAR; PG8_MMA(0, 0, At, B0); PG8_MMA(0, 1, At, B1); PG8_BAR; PG8_SCHED;
	s_setprio 1
	v_mfma_f32_16x16x32_bf16 v[62:65], v[162:165], v[212:215], v[62:65]
	v_mfma_f32_16x16x32_bf16 v[58:61], v[170:173], v[212:215], v[58:61]
	v_mfma_f32_16x16x32_bf16 v[46:49], v[162:165], v[220:223], v[46:49]
	v_mfma_f32_16x16x32_bf16 v[42:45], v[170:173], v[220:223], v[42:45]
	v_mfma_f32_16x16x32_bf16 v[30:33], v[162:165], v[228:231], v[30:33]
	v_mfma_f32_16x16x32_bf16 v[26:29], v[170:173], v[228:231], v[26:29]
	v_mfma_f32_16x16x32_bf16 v[14:17], v[162:165], v[236:239], v[14:17]
	v_mfma_f32_16x16x32_bf16 v[10:13], v[170:173], v[236:239], v[10:13]
	s_setprio 0
	s_setprio 1
	v_mfma_f32_16x16x32_bf16 v[62:65], v[166:169], v[216:219], v[62:65]
	v_mfma_f32_16x16x32_bf16 v[58:61], v[174:177], v[216:219], v[58:61]
	v_mfma_f32_16x16x32_bf16 v[46:49], v[166:169], v[224:227], v[46:49]
	v_mfma_f32_16x16x32_bf16 v[42:45], v[174:177], v[224:227], v[42:45]
	v_mfma_f32_16x16x32_bf16 v[30:33], v[166:169], v[232:235], v[30:33]
	v_mfma_f32_16x16x32_bf16 v[26:29], v[174:177], v[232:235], v[26:29]
	v_mfma_f32_16x16x32_bf16 v[14:17], v[166:169], v[240:243], v[14:17]
	v_mfma_f32_16x16x32_bf16 v[10:13], v[174:177], v[240:243], v[10:13]
	s_setprio 0
	s_setprio 1
	v_mfma_f32_16x16x32_bf16 v[54:57], v[178:181], v[212:215], v[54:57]
	v_mfma_f32_16x16x32_bf16 v[50:53], v[204:207], v[212:215], v[50:53]
	v_mfma_f32_16x16x32_bf16 v[38:41], v[178:181], v[220:223], v[38:41]
	v_mfma_f32_16x16x32_bf16 v[34:37], v[204:207], v[220:223], v[34:37]
	v_mfma_f32_16x16x32_bf16 v[22:25], v[178:181], v[228:231], v[22:25]
	v_mfma_f32_16x16x32_bf16 v[18:21], v[204:207], v[228:231], v[18:21]
	v_mfma_f32_16x16x32_bf16 v[6:9], v[178:181], v[236:239], v[6:9]
	v_mfma_f32_16x16x32_bf16 v[2:5], v[204:207], v[236:239], v[2:5]
	s_setprio 0
	s_setprio 1
	v_mfma_f32_16x16x32_bf16 v[54:57], v[182:185], v[216:219], v[54:57]
	v_mfma_f32_16x16x32_bf16 v[50:53], v[208:211], v[216:219], v[50:53]
	v_mfma_f32_16x16x32_bf16 v[38:41], v[182:185], v[224:227], v[38:41]
	v_mfma_f32_16x16x32_bf16 v[34:37], v[208:211], v[224:227], v[34:37]
	v_mfma_f32_16x16x32_bf16 v[22:25], v[182:185], v[232:235], v[22:25]
	v_mfma_f32_16x16x32_bf16 v[18:21], v[208:211], v[232:235], v[18:21]
	v_mfma_f32_16x16x32_bf16 v[6:9], v[182:185], v[240:243], v[6:9]
	v_mfma_f32_16x16x32_bf16 v[2:5], v[208:211], v[240:243], v[2:5]
	s_setprio 0
	s_barrier
	s_add_i32 s47, 0, 0x18000
	s_add_i32 s76, 0, 0x1c000
	v_add_u32_e32 v174, s47, v143
	v_add_u32_e32 v203, s76, v143
	ds_read_b128 v[162:165], v174
	ds_read_b128 v[166:169], v174 offset:1024
	ds_read_b128 v[170:173], v174 offset:2048
	ds_read_b128 v[174:177], v174 offset:3072
	ds_read_b128 v[178:181], v203
	ds_read_b128 v[182:185], v203 offset:1024
	ds_read_b128 v[204:207], v203 offset:2048
	ds_read_b128 v[208:211], v203 offset:3072
	s_add_u32 s58, s58, 0x80000
	s_addc_u32 s59, s59, 0
	s_mov_b32 m0, s67
	v_lshl_add_u64 v[248:249], s[58:59], 0, v[150:151]
	ds_read_b128 v[212:215], v161 offset:32768
	ds_read_b128 v[216:219], v161 offset:33792
	ds_read_b128 v[220:223], v161 offset:34816
	ds_read_b128 v[224:227], v161 offset:35840
	ds_read_b128 v[228:231], v161 offset:36864
	ds_read_b128 v[232:235], v161 offset:37888
	ds_read_b128 v[236:239], v161 offset:38912
	ds_read_b128 v[240:243], v161 offset:39936
	global_load_lds_dwordx4 v[248:249], off
	v_lshl_add_u64 v[248:249], s[58:59], 0, v[146:147]
	s_mov_b32 m0, s4
	s_nop 0
	global_load_lds_dwordx4 v[248:249], off
	s_waitcnt vmcnt(8)
	s_waitcnt lgkmcnt(0)
	s_barrier
	s_setprio 1
	v_mfma_f32_16x16x32_bf16 v[126:129], v[162:165], v[212:215], v[126:129]
	v_mfma_f32_16x16x32_bf16 v[122:125], v[170:173], v[212:215], v[122:125]
	v_mfma_f32_16x16x32_bf16 v[110:113], v[162:165], v[220:223], v[110:113]
	v_mfma_f32_16x16x32_bf16 v[106:109], v[170:173], v[220:223], v[106:109]
	v_mfma_f32_16x16x32_bf16 v[94:97], v[162:165], v[228:231], v[94:97]
	v_mfma_f32_16x16x32_bf16 v[90:93], v[170:173], v[228:231], v[90:93]
	v_mfma_f32_16x16x32_bf16 v[78:81], v[162:165], v[236:239], v[78:81]
	v_mfma_f32_16x16x32_bf16 v[74:77], v[170:173], v[236:239], v[74:77]
	s_setprio 0
	s_setprio 1
	v_mfma_f32_16x16x32_bf16 v[126:129], v[166:169], v[216:219], v[126:129]
	v_mfma_f32_16x16x32_bf16 v[122:125], v[174:177], v[216:219], v[122:125]
	v_mfma_f32_16x16x32_bf16 v[110:113], v[166:169], v[224:227], v[110:113]
	v_mfma_f32_16x16x32_bf16 v[106:109], v[174:177], v[224:227], v[106:109]
	v_mfma_f32_16x16x32_bf16 v[94:97], v[166:169], v[232:235], v[94:97]
	v_mfma_f32_16x16x32_bf16 v[90:93], v[174:177], v[232:235], v[90:93]
	v_mfma_f32_16x16x32_bf16 v[78:81], v[166:169], v[240:243], v[78:81]
	v_mfma_f32_16x16x32_bf16 v[74:77], v[174:177], v[240:243], v[74:77]
	s_setprio 0
	s_setprio 1
	v_mfma_f32_16x16x32_bf16 v[118:121], v[178:181], v[212:215], v[118:121]
	v_mfma_f32_16x16x32_bf16 v[114:117], v[204:207], v[212:215], v[114:117]
	v_mfma_f32_16x16x32_bf16 v[102:105], v[178:181], v[220:223], v[102:105]
	v_mfma_f32_16x16x32_bf16 v[98:101], v[204:207], v[220:223], v[98:101]
	v_mfma_f32_16x16x32_bf16 v[86:89], v[178:181], v[228:231], v[86:89]
	v_mfma_f32_16x16x32_bf16 v[82:85], v[204:207], v[228:231], v[82:85]
	v_mfma_f32_16x16x32_bf16 v[70:73], v[178:181], v[236:239], v[70:73]
	v_mfma_f32_16x16x32_bf16 v[66:69], v[204:207], v[236:239], v[66:69]
	s_setprio 0
	s_setprio 1
	v_mfma_f32_16x16x32_bf16 v[118:121], v[182:185], v[216:219], v[118:121]
	v_mfma_f32_16x16x32_bf16 v[114:117], v[208:211], v[216:219], v[114:117]
	v_mfma_f32_16x16x32_bf16 v[102:105], v[182:185], v[224:227], v[102:105]
	v_mfma_f32_16x16x32_bf16 v[98:101], v[208:211], v[224:227], v[98:101]
	v_mfma_f32_16x16x32_bf16 v[86:89], v[182:185], v[232:235], v[86:89]
	v_mfma_f32_16x16x32_bf16 v[82:85], v[208:211], v[232:235], v[82:85]
	v_mfma_f32_16x16x32_bf16 v[70:73], v[182:185], v[240:243], v[70:73]
	v_mfma_f32_16x16x32_bf16 v[66:69], v[208:211], v[240:243], v[66:69]
	s_setprio 0
	s_barrier
; #define PG8_STAGE(bufoff, gbase, voff) do { _Pragma("unroll") for (int _i = 0; _i < 2; ++_i) \
;         __builtin_amdgcn_global_load_lds((const unsigned*)((const char*)(gbase) + (voff)[_i]), (PG8_LAS unsigned*)(lds + (bufoff) + ldsw + _i * 8192), 16, 0, 0); } while (0)
; #define PG8_LDA(dst, b, h) do { _Pragma("unroll") for (int m = 0; m < 4; ++m) _Pragma("unroll") for (int k = 0; k < 2; ++k) dst[m][k] = *(const PG8_LAS bf16x8*)(lds + PG8_SA(b, h) + aoff + m * 2048 + k * 1024); } while (0)
; #define PG8_MMA(ai, bj, At, Bt) do { __builtin_amdgcn_s_setprio(1); _Pragma("unroll") for (int m = 0; m < 4; ++m) _Pragma("unroll") for (int n = 0; n < 2; ++n) _Pragma("unroll") for (int k = 0; k < 2; ++k) \
;         acc[ai][bj][m][n] = __builtin_amdgcn_mfma_f32_16x16x32_bf16(Bt[n][k], At[m][k], acc[ai][bj][m][n], 0, 0, 0); __builtin_amdgcn_s_setprio(0); } while (0)
; #define PG8_WAIT_V(n) asm volatile("s_waitcnt vmcnt(" #n ")" ::: "memory")
; #define PG8_WAIT_L(n) asm volatile("s_waitcnt lgkmcnt(" #n ")" ::: "memory")
; #define PG8_BAR __builtin_amdgcn_s_barrier()
; #define PG8_SCHED __builtin_amdgcn_sched_barrier(0)
; template <class Epi, class Sched, bool ALIGN_EPI = false, bool SP2 = false>
; __device__ __forceinline__ void gemm_phase(PG8_LAS unsigned char* lds, const Gemm g, const Sched& S, const Epi& E) {
;     ...
;             PG8_LDA(At, 1, 1); PG8_STAGE(PG8_SB(1, 0), b3, voffB); PG8_STAGE(PG8_SB(1, 1), b3 + hstep, voffB); PG8_STAGE(PG8_SA(1, 0), a3, voffA);
;             PG8_WAIT_V(8); PG8_WAIT_L(0); PG8_BAR; PG8_MMA(1, 0, At, B0); PG8_MMA(1, 1, At, B1); PG8_BAR; PG8_SCHED;
;     ...
;         if constexpr (ALIGN_EPI) { if (wr == 0) PG8_BAR; }
	s_add_i32 s47, s47, s54
	v_lshl_add_u64 v[158:159], v[158:159], 0, s[68:69]
	s_mov_b32 m0, s47
	ds_read_b128 v[212:215], v161 offset:49152
	ds_read_b128 v[216:219], v161 offset:50176
	ds_read_b128 v[220:223], v161 offset:51200
	ds_read_b128 v[224:227], v161 offset:52224
	ds_read_b128 v[228:231], v161 offset:53248
	ds_read_b128 v[232:235], v161 offset:54272
	ds_read_b128 v[236:239], v161 offset:55296
	ds_read_b128 v[240:243], v161 offset:56320
	global_load_lds_dwordx4 v[158:159], off
	s_add_i32 m0, s47, 0x2000
	s_add_u32 s18, s18, 0x80080
	v_lshl_add_u64 v[158:159], v[186:187], 0, s[68:69]
	s_addc_u32 s19, s19, 0
	s_add_i32 s47, s76, s54
	global_load_lds_dwordx4 v[158:159], off
	v_lshl_add_u64 v[158:159], s[18:19], 0, v[148:149]
	s_mov_b32 m0, s47
	s_nop 0
	global_load_lds_dwordx4 v[158:159], off
	v_lshl_add_u64 v[158:159], s[18:19], 0, v[144:145]
	s_add_i32 m0, s47, 0x2000
	s_nop 0
	global_load_lds_dwordx4 v[158:159], off
	v_lshl_add_u64 v[158:159], v[244:245], 0, s[68:69]
	s_mov_b32 m0, s5
	s_nop 0
	global_load_lds_dwordx4 v[158:159], off
	v_lshl_add_u64 v[158:159], v[246:247], 0, s[68:69]
	s_mov_b32 m0, s57
	s_nop 0
	global_load_lds_dwordx4 v[158:159], off
	s_waitcnt vmcnt(8)
	s_waitcnt lgkmcnt(0)
	s_barrier
	s_setprio 1
	v_mfma_f32_16x16x32_bf16 v[62:65], v[162:165], v[212:215], v[62:65]
	v_mfma_f32_16x16x32_bf16 v[58:61], v[170:173], v[212:215], v[58:61]
	v_mfma_f32_16x16x32_bf16 v[46:49], v[162:165], v[220:223], v[46:49]
	v_mfma_f32_16x16x32_bf16 v[42:45], v[170:173], v[220:223], v[42:45]
	v_mfma_f32_16x16x32_bf16 v[30:33], v[162:165], v[228:231], v[30:33]
	v_mfma_f32_16x16x32_bf16 v[26:29], v[170:173], v[228:231], v[26:29]
	v_mfma_f32_16x16x32_bf16 v[14:17], v[162:165], v[236:239], v[14:17]
	v_mfma_f32_16x16x32_bf16 v[10:13], v[170:173], v[236:239], v[10:13]
	s_setprio 0
	s_setprio 1
	v_mfma_f32_16x16x32_bf16 v[62:65], v[166:169], v[216:219], v[62:65]
	v_mfma_f32_16x16x32_bf16 v[58:61], v[174:177], v[216:219], v[58:61]
	v_mfma_f32_16x16x32_bf16 v[46:49], v[166:169], v[224:227], v[46:49]
	v_mfma_f32_16x16x32_bf16 v[42:45], v[174:177], v[224:227], v[42:45]
	v_mfma_f32_16x16x32_bf16 v[30:33], v[166:169], v[232:235], v[30:33]
	v_mfma_f32_16x16x32_bf16 v[26:29], v[174:177], v[232:235], v[26:29]
	v_mfma_f32_16x16x32_bf16 v[14:17], v[166:169], v[240:243], v[14:17]
	v_mfma_f32_16x16x32_bf16 v[10:13], v[174:177], v[240:243], v[10:13]
	s_setprio 0
	s_setprio 1
	v_mfma_f32_16x16x32_bf16 v[54:57], v[178:181], v[212:215], v[54:57]
	v_mfma_f32_16x16x32_bf16 v[50:53], v[204:207], v[212:215], v[50:53]
	v_mfma_f32_16x16x32_bf16 v[38:41], v[178:181], v[220:223], v[38:41]
	v_mfma_f32_16x16x32_bf16 v[34:37], v[204:207], v[220:223], v[34:37]
	v_mfma_f32_16x16x32_bf16 v[22:25], v[178:181], v[228:231], v[22:25]
	v_mfma_f32_16x16x32_bf16 v[18:21], v[204:207], v[228:231], v[18:21]
	v_mfma_f32_16x16x32_bf16 v[6:9], v[178:181], v[236:239], v[6:9]
	v_mfma_f32_16x16x32_bf16 v[2:5], v[204:207], v[236:239], v[2:5]
	s_setprio 0
	s_setprio 1
	v_mfma_f32_16x16x32_bf16 v[54:57], v[182:185], v[216:219], v[54:57]
	v_mfma_f32_16x16x32_bf16 v[50:53], v[208:211], v[216:219], v[50:53]
	v_mfma_f32_16x16x32_bf16 v[38:41], v[182:185], v[224:227], v[38:41]
	v_mfma_f32_16x16x32_bf16 v[34:37], v[208:211], v[224:227], v[34:37]
	v_mfma_f32_16x16x32_bf16 v[22:25], v[182:185], v[232:235], v[22:25]
	v_mfma_f32_16x16x32_bf16 v[18:21], v[208:211], v[232:235], v[18:21]
	v_mfma_f32_16x16x32_bf16 v[6:9], v[182:185], v[240:243], v[6:9]
	v_mfma_f32_16x16x32_bf16 v[2:5], v[208:211], v[240:243], v[2:5]
	s_setprio 0
	s_barrier
	s_add_i32 s46, s46, 2
	s_add_u32 s0, s0, 0x100
	s_addc_u32 s1, s1, 0
	s_add_u32 s78, s78, 0x100
	s_addc_u32 s79, s79, 0
	s_cmp_gt_u32 s46, 29
	s_cbranch_scc0 .LBB0_76
	s_and_b64 vcc, exec, s[42:43]
	s_cbranch_vccz .LBB0_79
	s_barrier

; #define PG8_STAGE(bufoff, gbase, voff) do { _Pragma("unroll") for (int _i = 0; _i < 2; ++_i) \
;         __builtin_amdgcn_global_load_lds((const unsigned*)((const char*)(gbase) + (voff)[_i]), (PG8_LAS unsigned*)(lds + (bufoff) + ldsw + _i * 8192), 16, 0, 0); } while (0)
; #define PG8_LDA(dst, b, h) do { _Pragma("unroll") for (int m = 0; m < 4; ++m) _Pragma("unroll") for (int k = 0; k < 2; ++k) dst[m][k] = *(const PG8_LAS bf16x8*)(lds + PG8_SA(b, h) + aoff + m * 2048 + k * 1024); } while (0)
; #define PG8_LDB(dst, b, h) do { _Pragma("unroll") for (int n = 0; n < 2; ++n) _Pragma("unroll") for (int k = 0; k < 2; ++k) dst[n][k] = *(const PG8_LAS bf16x8*)(lds + PG8_SB(b, h) + boff + n * 2048 + k * 1024); } while (0)
; #define PG8_WAIT_V(n) asm volatile("s_waitcnt vmcnt(" #n ")" ::: "memory")
; #define PG8_WAIT_L(n) asm volatile("s_waitcnt lgkmcnt(" #n ")" ::: "memory")
; #define PG8_BAR __builtin_amdgcn_s_barrier()
; #define PG8_SCHED __builtin_amdgcn_sched_barrier(0)
; template <class Epi, class Sched, bool ALIGN_EPI = false, bool SP2 = false>
; __device__ __forceinline__ void gemm_phase(PG8_LAS unsigned char* lds, const Gemm g, const Sched& S, const Epi& E) {
;     ...
;         const char* nA = has_next ? (const char*)g.A + (size_t)nxt.pm * tstep : cA; const char* nB = has_next ? (const char*)g.Bt + (size_t)nxt.pn * tstep : cB;
;         for (int t = 0; t < nt; t += 2) {
;             const bool last = (t == nt - 2);
;             const char* a1 = cA + (size_t)(t + 1) * kstep;
;             const char* a2 = last ? nA : cA + (size_t)(t + 2) * kstep; const char* b2 = last ? nB : cB + (size_t)(t + 2) * kstep;
;             const char* a3 = a2 + kstep; const char* b3 = b2 + kstep;
;             if (last && has_next) S.a_ready(nxt);
;             if constexpr (SP2) {
;             PG8_LDB(B0, 0, 0); PG8_LDB(B1, 0, 1); PG8_SCHED; PG8_LDA(At, 0, 0); PG8_STAGE(PG8_SA(1, 1), a1 + hstep, voffA);
;             PG8_WAIT_V(8); PG8_WAIT_L(0); PG8_BAR; PG8_MMA(0, 0, At, B0); PG8_MMA(0, 1, At, B1); PG8_BAR; PG8_SCHED;
;             PG8_LDA(At, 0, 1); PG8_STAGE(PG8_SB(0, 0), b2, voffB); PG8_STAGE(PG8_SB(0, 1), b2 + hstep, voffB); PG8_STAGE(PG8_SA(0, 0), a2, voffA);
;             PG8_WAIT_V(8); PG8_WAIT_L(0); PG8_BAR; PG8_MMA(1, 0, At, B0); PG8_MMA(1, 1, At, B1); PG8_BAR; PG8_SCHED;
.LBB0_98:
	s_add_u32 s40, vcc_lo, 0xfff80080
	s_addc_u32 s41, vcc_hi, -1
	s_add_i32 s47, 0, 0x10000
	s_cmp_eq_u32 s46, 28
	s_cselect_b32 s59, s97, s41
	s_cselect_b32 s58, s84, s40
	s_cselect_b32 s41, s85, s79
	s_cselect_b32 s40, s95, s78
	s_add_i32 s80, 0, 0x14000
	v_add_u32_e32 v170, s47, v143
	v_add_u32_e32 v186, s80, v143
	ds_read_b128 v[156:159], v170
	ds_read_b128 v[162:165], v170 offset:1024
	ds_read_b128 v[166:169], v170 offset:2048
	ds_read_b128 v[170:173], v170 offset:3072
	ds_read_b128 v[174:177], v186
	ds_read_b128 v[178:181], v186 offset:1024
	ds_read_b128 v[182:185], v186 offset:2048
	ds_read_b128 v[204:207], v186 offset:3072
	v_lshl_add_u64 v[186:187], vcc, 0, v[152:153]
	s_add_i32 m0, s5, 0xc000
	ds_read_b128 v[208:211], v161
	ds_read_b128 v[212:215], v161 offset:1024
	ds_read_b128 v[216:219], v161 offset:2048
	ds_read_b128 v[220:223], v161 offset:3072
	ds_read_b128 v[224:227], v161 offset:4096
	ds_read_b128 v[228:231], v161 offset:5120
	ds_read_b128 v[232:235], v161 offset:6144
	ds_read_b128 v[236:239], v161 offset:7168
	global_load_lds_dwordx4 v[186:187], off
	v_lshl_add_u64 v[186:187], vcc, 0, v[154:155]
	s_add_i32 m0, s5, 0xe000
	s_nop 0
	global_load_lds_dwordx4 v[186:187], off
	s_waitcnt vmcnt(8)
	s_waitcnt lgkmcnt(0)
	s_barrier
	s_setprio 1
	v_mfma_f32_16x16x32_bf16 v[126:129], v[156:159], v[208:211], v[126:129]
	v_mfma_f32_16x16x32_bf16 v[122:125], v[166:169], v[208:211], v[122:125]
	v_mfma_f32_16x16x32_bf16 v[110:113], v[156:159], v[216:219], v[110:113]
	v_mfma_f32_16x16x32_bf16 v[106:109], v[166:169], v[216:219], v[106:109]
	v_mfma_f32_16x16x32_bf16 v[94:97], v[156:159], v[224:227], v[94:97]
	v_mfma_f32_16x16x32_bf16 v[90:93], v[166:169], v[224:227], v[90:93]
	v_mfma_f32_16x16x32_bf16 v[78:81], v[156:159], v[232:235], v[78:81]
	v_mfma_f32_16x16x32_bf16 v[74:77], v[166:169], v[232:235], v[74:77]
	s_setprio 0
	s_setprio 1
	v_mfma_f32_16x16x32_bf16 v[126:129], v[162:165], v[212:215], v[126:129]
	v_mfma_f32_16x16x32_bf16 v[122:125], v[170:173], v[212:215], v[122:125]
	v_mfma_f32_16x16x32_bf16 v[110:113], v[162:165], v[220:223], v[110:113]
	v_mfma_f32_16x16x32_bf16 v[106:109], v[170:173], v[220:223], v[106:109]
	v_mfma_f32_16x16x32_bf16 v[94:97], v[162:165], v[228:231], v[94:97]
	v_mfma_f32_16x16x32_bf16 v[90:93], v[170:173], v[228:231], v[90:93]
	v_mfma_f32_16x16x32_bf16 v[78:81], v[162:165], v[236:239], v[78:81]
	v_mfma_f32_16x16x32_bf16 v[74:77], v[170:173], v[236:239], v[74:77]
	s_setprio 0
	s_setprio 1
	v_mfma_f32_16x16x32_bf16 v[118:121], v[174:177], v[208:211], v[118:121]
	v_mfma_f32_16x16x32_bf16 v[114:117], v[182:185], v[208:211], v[114:117]
	v_mfma_f32_16x16x32_bf16 v[102:105], v[174:177], v[216:219], v[102:105]
	v_mfma_f32_16x16x32_bf16 v[98:101], v[182:185], v[216:219], v[98:101]
	v_mfma_f32_16x16x32_bf16 v[86:89], v[174:177], v[224:227], v[86:89]
	v_mfma_f32_16x16x32_bf16 v[82:85], v[182:185], v[224:227], v[82:85]
	v_mfma_f32_16x16x32_bf16 v[70:73], v[174:177], v[232:235], v[70:73]
	v_mfma_f32_16x16x32_bf16 v[66:69], v[182:185], v[232:235], v[66:69]
	s_setprio 0
	s_setprio 1
	v_mfma_f32_16x16x32_bf16 v[118:121], v[178:181], v[212:215], v[118:121]
	v_mfma_f32_16x16x32_bf16 v[114:117], v[204:207], v[212:215], v[114:117]
	v_mfma_f32_16x16x32_bf16 v[102:105], v[178:181], v[220:223], v[102:105]
	v_mfma_f32_16x16x32_bf16 v[98:101], v[204:207], v[220:223], v[98:101]
	v_mfma_f32_16x16x32_bf16 v[86:89], v[178:181], v[228:231], v[86:89]
	v_mfma_f32_16x16x32_bf16 v[82:85], v[204:207], v[228:231], v[82:85]
	v_mfma_f32_16x16x32_bf16 v[70:73], v[178:181], v[236:239], v[70:73]
	v_mfma_f32_16x16x32_bf16 v[66:69], v[204:207], v[236:239], v[66:69]
	s_setprio 0
	s_barrier
	s_add_i32 s47, s47, s4
	v_lshl_add_u64 v[186:187], s[40:41], 0, v[148:149]
	s_mov_b32 m0, s47
	ds_read_b128 v[208:211], v161 offset:16384
	ds_read_b128 v[212:215], v161 offset:17408
	ds_read_b128 v[216:219], v161 offset:18432
	ds_read_b128 v[220:223], v161 offset:19456
	ds_read_b128 v[224:227], v161 offset:20480
	ds_read_b128 v[228:231], v161 offset:21504
	ds_read_b128 v[232:235], v161 offset:22528
	ds_read_b128 v[236:239], v161 offset:23552
	global_load_lds_dwordx4 v[186:187], off
	s_add_i32 m0, s47, 0x2000
	s_add_u32 s76, s40, 0x80000
	v_lshl_add_u64 v[240:241], s[40:41], 0, v[144:145]
	s_addc_u32 s77, s41, 0
	s_add_i32 s47, s80, s4
	global_load_lds_dwordx4 v[240:241], off
	v_lshl_add_u64 v[242:243], s[76:77], 0, v[148:149]
	s_mov_b32 m0, s47
	v_lshl_add_u64 v[244:245], s[58:59], 0, v[146:147]
	global_load_lds_dwordx4 v[242:243], off
	v_lshl_add_u64 v[242:243], s[76:77], 0, v[144:145]
	s_add_i32 m0, s47, 0x2000
	s_nop 0
	global_load_lds_dwordx4 v[242:243], off
	v_lshl_add_u64 v[242:243], s[58:59], 0, v[150:151]
	s_mov_b32 m0, s5
	s_nop 0
	global_load_lds_dwordx4 v[242:243], off
	s_mov_b32 m0, s30
	s_nop 0
	global_load_lds_dwordx4 v[244:245], off
	s_waitcnt vmcnt(8)
	s_waitcnt lgkmcnt(0)
	s_barrier
; #define PG8_STAGE(bufoff, gbase, voff) do { _Pragma("unroll") for (int _i = 0; _i < 2; ++_i) \
;         __builtin_amdgcn_global_load_lds((const unsigned*)((const char*)(gbase) + (voff)[_i]), (PG8_LAS unsigned*)(lds + (bufoff) + ldsw + _i * 8192), 16, 0, 0); } while (0)
; #define PG8_LDA(dst, b, h) do { _Pragma("unroll") for (int m = 0; m < 4; ++m) _Pragma("unroll") for (int k = 0; k < 2; ++k) dst[m][k] = *(const PG8_LAS bf16x8*)(lds + PG8_SA(b, h) + aoff + m * 2048 + k * 1024); } while (0)
; #define PG8_LDB(dst, b, h) do { _Pragma("unroll") for (int n = 0; n < 2; ++n) _Pragma("unroll") for (int k = 0; k < 2; ++k) dst[n][k] = *(const PG8_LAS bf16x8*)(lds + PG8_SB(b, h) + boff + n * 2048 + k * 1024); } while (0)
; #define PG8_MMA(ai, bj, At, Bt) do { __builtin_amdgcn_s_setprio(1); _Pragma("unroll") for (int m = 0; m < 4; ++m) _Pragma("unroll") for (int n = 0; n < 2; ++n) _Pragma("unroll") for (int k = 0; k < 2; ++k) \
;         acc[ai][bj][m][n] = __builtin_amdgcn_mfma_f32_16x16x32_bf16(Bt[n][k], At[m][k], acc[ai][bj][m][n], 0, 0, 0); __builtin_amdgcn_s_setprio(0); } while (0)
; #define PG8_WAIT_V(n) asm volatile("s_waitcnt vmcnt(" #n ")" ::: "memory")
; #define PG8_WAIT_L(n) asm volatile("s_waitcnt lgkmcnt(" #n ")" ::: "memory")
; #define PG8_BAR __builtin_amdgcn_s_barrier()
; #define PG8_SCHED __builtin_amdgcn_sched_barrier(0)
; template <class Epi, class Sched, bool ALIGN_EPI = false, bool SP2 = false>
; __device__ __forceinline__ void gemm_phase(PG8_LAS unsigned char* lds, const Gemm g, const Sched& S, const Epi& E) {
;     ...
;             PG8_WAIT_V(8); PG8_WAIT_L(0); PG8_BAR; PG8_MMA(1, 0, At, B0); PG8_MMA(1, 1, At, B1); PG8_BAR; PG8_SCHED;
;             PG8_LDB(B0, 1, 0); PG8_LDB(B1, 1, 1); PG8_SCHED; PG8_LDA(At, 1, 0); PG8_STAGE(PG8_SA(0, 1), a2 + hstep, voffA);
;             PG8_WAIT_V(8); PG8_WAIT_L(0); PG8_BAR; PG8_MMA(0, 0, At, B0); PG8_MMA(0, 1, At, B1); PG8_BAR; PG8_SCHED;
	s_setprio 1
	v_mfma_f32_16x16x32_bf16 v[62:65], v[156:159], v[208:211], v[62:65]
	v_mfma_f32_16x16x32_bf16 v[58:61], v[166:169], v[208:211], v[58:61]
	v_mfma_f32_16x16x32_bf16 v[46:49], v[156:159], v[216:219], v[46:49]
	v_mfma_f32_16x16x32_bf16 v[42:45], v[166:169], v[216:219], v[42:45]
	v_mfma_f32_16x16x32_bf16 v[30:33], v[156:159], v[224:227], v[30:33]
	v_mfma_f32_16x16x32_bf16 v[26:29], v[166:169], v[224:227], v[26:29]
	v_mfma_f32_16x16x32_bf16 v[14:17], v[156:159], v[232:235], v[14:17]
	v_mfma_f32_16x16x32_bf16 v[10:13], v[166:169], v[232:235], v[10:13]
	s_setprio 0
	s_setprio 1
	v_mfma_f32_16x16x32_bf16 v[62:65], v[162:165], v[212:215], v[62:65]
	v_mfma_f32_16x16x32_bf16 v[58:61], v[170:173], v[212:215], v[58:61]
	v_mfma_f32_16x16x32_bf16 v[46:49], v[162:165], v[220:223], v[46:49]
	v_mfma_f32_16x16x32_bf16 v[42:45], v[170:173], v[220:223], v[42:45]
	v_mfma_f32_16x16x32_bf16 v[30:33], v[162:165], v[228:231], v[30:33]
	v_mfma_f32_16x16x32_bf16 v[26:29], v[170:173], v[228:231], v[26:29]
	v_mfma_f32_16x16x32_bf16 v[14:17], v[162:165], v[236:239], v[14:17]
	v_mfma_f32_16x16x32_bf16 v[10:13], v[170:173], v[236:239], v[10:13]
	s_setprio 0
	s_setprio 1
	v_mfma_f32_16x16x32_bf16 v[54:57], v[174:177], v[208:211], v[54:57]
	v_mfma_f32_16x16x32_bf16 v[50:53], v[182:185], v[208:211], v[50:53]
	v_mfma_f32_16x16x32_bf16 v[38:41], v[174:177], v[216:219], v[38:41]
	v_mfma_f32_16x16x32_bf16 v[34:37], v[182:185], v[216:219], v[34:37]
	v_mfma_f32_16x16x32_bf16 v[22:25], v[174:177], v[224:227], v[22:25]
	v_mfma_f32_16x16x32_bf16 v[18:21], v[182:185], v[224:227], v[18:21]
	v_mfma_f32_16x16x32_bf16 v[6:9], v[174:177], v[232:235], v[6:9]
	v_mfma_f32_16x16x32_bf16 v[2:5], v[182:185], v[232:235], v[2:5]
	s_setprio 0
	s_setprio 1
	v_mfma_f32_16x16x32_bf16 v[54:57], v[178:181], v[212:215], v[54:57]
	v_mfma_f32_16x16x32_bf16 v[50:53], v[204:207], v[212:215], v[50:53]
	v_mfma_f32_16x16x32_bf16 v[38:41], v[178:181], v[220:223], v[38:41]
	v_mfma_f32_16x16x32_bf16 v[34:37], v[204:207], v[220:223], v[34:37]
	v_mfma_f32_16x16x32_bf16 v[22:25], v[178:181], v[228:231], v[22:25]
	v_mfma_f32_16x16x32_bf16 v[18:21], v[204:207], v[228:231], v[18:21]
	v_mfma_f32_16x16x32_bf16 v[6:9], v[178:181], v[236:239], v[6:9]
	v_mfma_f32_16x16x32_bf16 v[2:5], v[204:207], v[236:239], v[2:5]
	s_setprio 0
	s_barrier
	s_add_i32 s47, 0, 0x18000
	s_add_i32 s76, 0, 0x1c000
	v_add_u32_e32 v170, s47, v143
	v_add_u32_e32 v203, s76, v143
	ds_read_b128 v[156:159], v170
	ds_read_b128 v[162:165], v170 offset:1024
	ds_read_b128 v[166:169], v170 offset:2048
	ds_read_b128 v[170:173], v170 offset:3072
	ds_read_b128 v[174:177], v203
	ds_read_b128 v[178:181], v203 offset:1024
	ds_read_b128 v[182:185], v203 offset:2048
	ds_read_b128 v[204:207], v203 offset:3072
	s_add_u32 s58, s58, 0x80000
	s_addc_u32 s59, s59, 0
	s_mov_b32 m0, s34
	v_lshl_add_u64 v[246:247], s[58:59], 0, v[150:151]
	ds_read_b128 v[208:211], v161 offset:32768
	ds_read_b128 v[212:215], v161 offset:33792
	ds_read_b128 v[216:219], v161 offset:34816
	ds_read_b128 v[220:223], v161 offset:35840
	ds_read_b128 v[224:227], v161 offset:36864
	ds_read_b128 v[228:231], v161 offset:37888
	ds_read_b128 v[232:235], v161 offset:38912
	ds_read_b128 v[236:239], v161 offset:39936
	global_load_lds_dwordx4 v[246:247], off
	v_lshl_add_u64 v[246:247], s[58:59], 0, v[146:147]
	s_mov_b32 m0, s57
	s_nop 0
	global_load_lds_dwordx4 v[246:247], off
	s_waitcnt vmcnt(8)
	s_waitcnt lgkmcnt(0)
	s_barrier
	s_setprio 1
	v_mfma_f32_16x16x32_bf16 v[126:129], v[156:159], v[208:211], v[126:129]
	v_mfma_f32_16x16x32_bf16 v[122:125], v[166:169], v[208:211], v[122:125]
	v_mfma_f32_16x16x32_bf16 v[110:113], v[156:159], v[216:219], v[110:113]
	v_mfma_f32_16x16x32_bf16 v[106:109], v[166:169], v[216:219], v[106:109]
	v_mfma_f32_16x16x32_bf16 v[94:97], v[156:159], v[224:227], v[94:97]
	v_mfma_f32_16x16x32_bf16 v[90:93], v[166:169], v[224:227], v[90:93]
	v_mfma_f32_16x16x32_bf16 v[78:81], v[156:159], v[232:235], v[78:81]
	v_mfma_f32_16x16x32_bf16 v[74:77], v[166:169], v[232:235], v[74:77]
	s_setprio 0
	s_setprio 1
	v_mfma_f32_16x16x32_bf16 v[126:129], v[162:165], v[212:215], v[126:129]
	v_mfma_f32_16x16x32_bf16 v[122:125], v[170:173], v[212:215], v[122:125]
	v_mfma_f32_16x16x32_bf16 v[110:113], v[162:165], v[220:223], v[110:113]
	v_mfma_f32_16x16x32_bf16 v[106:109], v[170:173], v[220:223], v[106:109]
	v_mfma_f32_16x16x32_bf16 v[94:97], v[162:165], v[228:231], v[94:97]
	v_mfma_f32_16x16x32_bf16 v[90:93], v[170:173], v[228:231], v[90:93]
	v_mfma_f32_16x16x32_bf16 v[78:81], v[162:165], v[236:239], v[78:81]
	v_mfma_f32_16x16x32_bf16 v[74:77], v[170:173], v[236:239], v[74:77]
	s_setprio 0
	s_setprio 1
	v_mfma_f32_16x16x32_bf16 v[118:121], v[174:177], v[208:211], v[118:121]
	v_mfma_f32_16x16x32_bf16 v[114:117], v[182:185], v[208:211], v[114:117]
	v_mfma_f32_16x16x32_bf16 v[102:105], v[174:177], v[216:219], v[102:105]
	v_mfma_f32_16x16x32_bf16 v[98:101], v[182:185], v[216:219], v[98:101]
	v_mfma_f32_16x16x32_bf16 v[86:89], v[174:177], v[224:227], v[86:89]
	v_mfma_f32_16x16x32_bf16 v[82:85], v[182:185], v[224:227], v[82:85]
	v_mfma_f32_16x16x32_bf16 v[70:73], v[174:177], v[232:235], v[70:73]
	v_mfma_f32_16x16x32_bf16 v[66:69], v[182:185], v[232:235], v[66:69]
	s_setprio 0
	s_setprio 1
	v_mfma_f32_16x16x32_bf16 v[118:121], v[178:181], v[212:215], v[118:121]
	v_mfma_f32_16x16x32_bf16 v[114:117], v[204:207], v[212:215], v[114:117]
	v_mfma_f32_16x16x32_bf16 v[102:105], v[178:181], v[220:223], v[102:105]
	v_mfma_f32_16x16x32_bf16 v[98:101], v[204:207], v[220:223], v[98:101]
	v_mfma_f32_16x16x32_bf16 v[86:89], v[178:181], v[228:231], v[86:89]
	v_mfma_f32_16x16x32_bf16 v[82:85], v[204:207], v[228:231], v[82:85]
	v_mfma_f32_16x16x32_bf16 v[70:73], v[178:181], v[236:239], v[70:73]
	v_mfma_f32_16x16x32_bf16 v[66:69], v[204:207], v[236:239], v[66:69]
	s_setprio 0
	s_barrier
; #define PG8_STAGE(bufoff, gbase, voff) do { _Pragma("unroll") for (int _i = 0; _i < 2; ++_i) \
;         __builtin_amdgcn_global_load_lds((const unsigned*)((const char*)(gbase) + (voff)[_i]), (PG8_LAS unsigned*)(lds + (bufoff) + ldsw + _i * 8192), 16, 0, 0); } while (0)
; #define PG8_LDA(dst, b, h) do { _Pragma("unroll") for (int m = 0; m < 4; ++m) _Pragma("unroll") for (int k = 0; k < 2; ++k) dst[m][k] = *(const PG8_LAS bf16x8*)(lds + PG8_SA(b, h) + aoff + m * 2048 + k * 1024); } while (0)
; #define PG8_MMA(ai, bj, At, Bt) do { __builtin_amdgcn_s_setprio(1); _Pragma("unroll") for (int m = 0; m < 4; ++m) _Pragma("unroll") for (int n = 0; n < 2; ++n) _Pragma("unroll") for (int k = 0; k < 2; ++k) \
;         acc[ai][bj][m][n] = __builtin_amdgcn_mfma_f32_16x16x32_bf16(Bt[n][k], At[m][k], acc[ai][bj][m][n], 0, 0, 0); __builtin_amdgcn_s_setprio(0); } while (0)
; #define PG8_WAIT_V(n) asm volatile("s_waitcnt vmcnt(" #n ")" ::: "memory")
; #define PG8_WAIT_L(n) asm volatile("s_waitcnt lgkmcnt(" #n ")" ::: "memory")
; #define PG8_BAR __builtin_amdgcn_s_barrier()
; #define PG8_SCHED __builtin_amdgcn_sched_barrier(0)
;     __device__ __forceinline__ void operator()(const f32x4 (&acc)[2][2][4][2], const Unit& u, int wr, int wc, int fr, int fq) const {
;     ...
;                 for (int bj = 0; bj < 2; ++bj) { const size_t off = row * DM + col0 + bj * HALF;
;                     f32x4 v0 = acc[ai][bj][m][0] + *(const f32x4*)(base + off), v1 = acc[ai][bj][m][1] + *(const f32x4*)(base + off + 4);
; template <class Epi, class Sched, bool ALIGN_EPI = false, bool SP2 = false>
; __device__ __forceinline__ void gemm_phase(PG8_LAS unsigned char* lds, const Gemm g, const Sched& S, const Epi& E) {
;     ...
;             PG8_LDA(At, 1, 1); PG8_STAGE(PG8_SB(1, 0), b3, voffB); PG8_STAGE(PG8_SB(1, 1), b3 + hstep, voffB); PG8_STAGE(PG8_SA(1, 0), a3, voffA);
;             PG8_WAIT_V(8); PG8_WAIT_L(0); PG8_BAR; PG8_MMA(1, 0, At, B0); PG8_MMA(1, 1, At, B1); PG8_BAR; PG8_SCHED;
;     ...
;         if constexpr (ALIGN_EPI) { if (wr == 0) PG8_BAR; }
	s_add_i32 s47, s47, s4
	v_lshl_add_u64 v[186:187], v[186:187], 0, s[68:69]
	s_mov_b32 m0, s47
	ds_read_b128 v[208:211], v161 offset:49152
	ds_read_b128 v[212:215], v161 offset:50176
	ds_read_b128 v[216:219], v161 offset:51200
	ds_read_b128 v[220:223], v161 offset:52224
	ds_read_b128 v[224:227], v161 offset:53248
	ds_read_b128 v[228:231], v161 offset:54272
	ds_read_b128 v[232:235], v161 offset:55296
	ds_read_b128 v[236:239], v161 offset:56320
	global_load_lds_dwordx4 v[186:187], off
	s_add_i32 m0, s47, 0x2000
	s_add_u32 s40, s40, 0x80080
	v_lshl_add_u64 v[186:187], v[240:241], 0, s[68:69]
	s_addc_u32 s41, s41, 0
	s_add_i32 s47, s76, s4
	global_load_lds_dwordx4 v[186:187], off
	v_lshl_add_u64 v[186:187], s[40:41], 0, v[148:149]
	s_mov_b32 m0, s47
	s_nop 0
	global_load_lds_dwordx4 v[186:187], off
	v_lshl_add_u64 v[186:187], s[40:41], 0, v[144:145]
	s_add_i32 m0, s47, 0x2000
	s_nop 0
	global_load_lds_dwordx4 v[186:187], off
	v_lshl_add_u64 v[186:187], v[242:243], 0, s[68:69]
	s_mov_b32 m0, s67
	s_nop 0
	global_load_lds_dwordx4 v[186:187], off
	v_lshl_add_u64 v[186:187], v[244:245], 0, s[68:69]
	s_mov_b32 m0, s28
	s_nop 0
	global_load_lds_dwordx4 v[186:187], off
	s_waitcnt vmcnt(8)
	s_waitcnt lgkmcnt(0)
	s_barrier
	s_setprio 1
	v_mfma_f32_16x16x32_bf16 v[62:65], v[156:159], v[208:211], v[62:65]
	v_mfma_f32_16x16x32_bf16 v[58:61], v[166:169], v[208:211], v[58:61]
	v_mfma_f32_16x16x32_bf16 v[46:49], v[156:159], v[216:219], v[46:49]
	v_mfma_f32_16x16x32_bf16 v[42:45], v[166:169], v[216:219], v[42:45]
	v_mfma_f32_16x16x32_bf16 v[30:33], v[156:159], v[224:227], v[30:33]
	v_mfma_f32_16x16x32_bf16 v[26:29], v[166:169], v[224:227], v[26:29]
	v_mfma_f32_16x16x32_bf16 v[14:17], v[156:159], v[232:235], v[14:17]
	v_mfma_f32_16x16x32_bf16 v[10:13], v[166:169], v[232:235], v[10:13]
	s_setprio 0
	s_setprio 1
	v_mfma_f32_16x16x32_bf16 v[62:65], v[162:165], v[212:215], v[62:65]
	v_mfma_f32_16x16x32_bf16 v[58:61], v[170:173], v[212:215], v[58:61]
	v_mfma_f32_16x16x32_bf16 v[46:49], v[162:165], v[220:223], v[46:49]
	v_mfma_f32_16x16x32_bf16 v[42:45], v[170:173], v[220:223], v[42:45]
	v_mfma_f32_16x16x32_bf16 v[30:33], v[162:165], v[228:231], v[30:33]
	v_mfma_f32_16x16x32_bf16 v[26:29], v[170:173], v[228:231], v[26:29]
	v_mfma_f32_16x16x32_bf16 v[14:17], v[162:165], v[236:239], v[14:17]
	v_mfma_f32_16x16x32_bf16 v[10:13], v[170:173], v[236:239], v[10:13]
	s_setprio 0
	s_setprio 1
	v_mfma_f32_16x16x32_bf16 v[54:57], v[174:177], v[208:211], v[54:57]
	v_mfma_f32_16x16x32_bf16 v[50:53], v[182:185], v[208:211], v[50:53]
	v_mfma_f32_16x16x32_bf16 v[38:41], v[174:177], v[216:219], v[38:41]
	v_mfma_f32_16x16x32_bf16 v[34:37], v[182:185], v[216:219], v[34:37]
	v_mfma_f32_16x16x32_bf16 v[22:25], v[174:177], v[224:227], v[22:25]
	v_mfma_f32_16x16x32_bf16 v[18:21], v[182:185], v[224:227], v[18:21]
	v_mfma_f32_16x16x32_bf16 v[6:9], v[174:177], v[232:235], v[6:9]
	v_mfma_f32_16x16x32_bf16 v[2:5], v[182:185], v[232:235], v[2:5]
	s_setprio 0
	s_setprio 1
	v_mfma_f32_16x16x32_bf16 v[54:57], v[178:181], v[212:215], v[54:57]
	v_mfma_f32_16x16x32_bf16 v[50:53], v[204:207], v[212:215], v[50:53]
	v_mfma_f32_16x16x32_bf16 v[38:41], v[178:181], v[220:223], v[38:41]
	v_mfma_f32_16x16x32_bf16 v[34:37], v[204:207], v[220:223], v[34:37]
	v_mfma_f32_16x16x32_bf16 v[22:25], v[178:181], v[228:231], v[22:25]
	v_mfma_f32_16x16x32_bf16 v[18:21], v[204:207], v[228:231], v[18:21]
	v_mfma_f32_16x16x32_bf16 v[6:9], v[178:181], v[236:239], v[6:9]
	v_mfma_f32_16x16x32_bf16 v[2:5], v[204:207], v[236:239], v[2:5]
	s_setprio 0
	s_barrier
	s_add_i32 s46, s46, 2
	s_add_u32 vcc_lo, vcc_lo, 0x100
	s_addc_u32 vcc_hi, vcc_hi, 0
	s_add_u32 s78, s78, 0x100
	s_addc_u32 s79, s79, 0
	s_cmp_gt_u32 s46, 29
	s_cbranch_scc0 .LBB0_98
	v_lshl_add_u32 v156, s73, 8, v1
	v_lshl_or_b32 v157, s54, 8, v160
	v_lshl_add_u32 v157, v156, 11, v157
	v_mov_b32_e32 v247, 0
	v_lshlrev_b32_e32 v246, 2, v157
	v_lshl_add_u64 v[162:163], s[8:9], 0, v[246:247]
	v_lshlrev_b32_e32 v246, 1, v157
	v_lshl_add_u64 v[244:245], s[70:71], 0, v[246:247]
	s_mov_b32 s41, 0
	global_load_dwordx4 v[164:167], v[162:163], off
	global_load_dwordx4 v[168:171], v[162:163], off offset:16
	global_load_dwordx4 v[172:175], v[162:163], off offset:512
	global_load_dwordx4 v[176:179], v[162:163], off offset:528
	s_mov_b32 s40, 0x20000
	v_lshl_add_u64 v[246:247], v[162:163], 0, s[40:41]
	global_load_dwordx4 v[180:183], v[246:247], off
	global_load_dwordx4 v[184:187], v[246:247], off offset:16
	global_load_dwordx4 v[204:207], v[246:247], off offset:512
	global_load_dwordx4 v[208:211], v[246:247], off offset:528
	s_mov_b32 s40, 0x40000
	v_lshl_add_u64 v[246:247], v[162:163], 0, s[40:41]
	global_load_dwordx4 v[212:215], v[246:247], off
	global_load_dwordx4 v[216:219], v[246:247], off offset:16
	global_load_dwordx4 v[220:223], v[246:247], off offset:512
	global_load_dwordx4 v[224:227], v[246:247], off offset:528
	s_mov_b32 s40, 0x60000
	v_lshl_add_u64 v[246:247], v[162:163], 0, s[40:41]
	global_load_dwordx4 v[228:231], v[246:247], off
	global_load_dwordx4 v[232:235], v[246:247], off offset:16
	global_load_dwordx4 v[236:239], v[246:247], off offset:512
	global_load_dwordx4 v[240:243], v[246:247], off offset:528
	s_and_b64 vcc, exec, s[36:37]
	s_cbranch_vccz .Lx1_nobar
	s_barrier

; #define PG8_STAGE(bufoff, gbase, voff) do { _Pragma("unroll") for (int _i = 0; _i < 2; ++_i) \
;         __builtin_amdgcn_global_load_lds((const unsigned*)((const char*)(gbase) + (voff)[_i]), (PG8_LAS unsigned*)(lds + (bufoff) + ldsw + _i * 8192), 16, 0, 0); } while (0)
; #define PG8_LDA(dst, b, h) do { _Pragma("unroll") for (int m = 0; m < 4; ++m) _Pragma("unroll") for (int k = 0; k < 2; ++k) dst[m][k] = *(const PG8_LAS bf16x8*)(lds + PG8_SA(b, h) + aoff + m * 2048 + k * 1024); } while (0)
; #define PG8_LDB(dst, b, h) do { _Pragma("unroll") for (int n = 0; n < 2; ++n) _Pragma("unroll") for (int k = 0; k < 2; ++k) dst[n][k] = *(const PG8_LAS bf16x8*)(lds + PG8_SB(b, h) + boff + n * 2048 + k * 1024); } while (0)
; #define PG8_WAIT_V(n) asm volatile("s_waitcnt vmcnt(" #n ")" ::: "memory")
; #define PG8_WAIT_L(n) asm volatile("s_waitcnt lgkmcnt(" #n ")" ::: "memory")
; #define PG8_BAR __builtin_amdgcn_s_barrier()
; #define PG8_SCHED __builtin_amdgcn_sched_barrier(0)
; template <class Epi, class Sched, bool ALIGN_EPI = false, bool SP2 = false>
; __device__ __forceinline__ void gemm_phase(PG8_LAS unsigned char* lds, const Gemm g, const Sched& S, const Epi& E) {
;     ...
;         const char* nA = has_next ? (const char*)g.A + (size_t)nxt.pm * tstep : cA; const char* nB = has_next ? (const char*)g.Bt + (size_t)nxt.pn * tstep : cB;
;         for (int t = 0; t < nt; t += 2) {
;             const bool last = (t == nt - 2);
;             const char* a1 = cA + (size_t)(t + 1) * kstep;
;             const char* a2 = last ? nA : cA + (size_t)(t + 2) * kstep; const char* b2 = last ? nB : cB + (size_t)(t + 2) * kstep;
;             const char* a3 = a2 + kstep; const char* b3 = b2 + kstep;
;             if (last && has_next) S.a_ready(nxt);
;             if constexpr (SP2) {
;             PG8_LDB(B0, 0, 0); PG8_LDB(B1, 0, 1); PG8_SCHED; PG8_LDA(At, 0, 0); PG8_STAGE(PG8_SA(1, 1), a1 + hstep, voffA);
;             PG8_WAIT_V(8); PG8_WAIT_L(0); PG8_BAR; PG8_MMA(0, 0, At, B0); PG8_MMA(0, 1, At, B1); PG8_BAR; PG8_SCHED;
;             PG8_LDA(At, 0, 1); PG8_STAGE(PG8_SB(0, 0), b2, voffB); PG8_STAGE(PG8_SB(0, 1), b2 + hstep, voffB); PG8_STAGE(PG8_SA(0, 0), a2, voffA);
;             PG8_WAIT_V(8); PG8_WAIT_L(0); PG8_BAR; PG8_MMA(1, 0, At, B0); PG8_MMA(1, 1, At, B1); PG8_BAR; PG8_SCHED;
.LBB0_136:
	s_add_u32 s18, s58, 0xfffe0080
	s_addc_u32 s19, s59, -1
	s_add_i32 s46, 0, 0x10000
	s_cmp_eq_u32 s79, 4
	s_cselect_b32 s63, s37, s19
	s_cselect_b32 s62, s73, s18
	s_cselect_b32 s19, s11, s78
	s_cselect_b32 s18, s84, s85
	s_add_i32 s76, 0, 0x14000
	v_add_u32_e32 v172, s46, v1
	v_add_u32_e32 v203, s76, v1
	ds_read_b128 v[160:163], v172
	ds_read_b128 v[164:167], v172 offset:1024
	ds_read_b128 v[168:171], v172 offset:2048
	ds_read_b128 v[172:175], v172 offset:3072
	ds_read_b128 v[176:179], v203
	ds_read_b128 v[180:183], v203 offset:1024
	ds_read_b128 v[184:187], v203 offset:2048
	ds_read_b128 v[204:207], v203 offset:3072
	v_lshl_add_u64 v[240:241], s[58:59], 0, v[156:157]
	s_add_i32 m0, s5, 0xc000
	ds_read_b128 v[208:211], v143
	ds_read_b128 v[212:215], v143 offset:1024
	ds_read_b128 v[216:219], v143 offset:2048
	ds_read_b128 v[220:223], v143 offset:3072
	ds_read_b128 v[224:227], v143 offset:4096
	ds_read_b128 v[228:231], v143 offset:5120
	ds_read_b128 v[232:235], v143 offset:6144
	ds_read_b128 v[236:239], v143 offset:7168
	global_load_lds_dwordx4 v[240:241], off
	v_lshl_add_u64 v[240:241], s[58:59], 0, v[158:159]
	s_add_i32 m0, s5, 0xe000
	s_nop 0
	global_load_lds_dwordx4 v[240:241], off
	s_waitcnt vmcnt(8)
	s_waitcnt lgkmcnt(0)
	s_barrier
	s_setprio 1
	v_mfma_f32_16x16x32_bf16 v[126:129], v[160:163], v[208:211], v[126:129]
	v_mfma_f32_16x16x32_bf16 v[122:125], v[168:171], v[208:211], v[122:125]
	v_mfma_f32_16x16x32_bf16 v[110:113], v[160:163], v[216:219], v[110:113]
	v_mfma_f32_16x16x32_bf16 v[106:109], v[168:171], v[216:219], v[106:109]
	v_mfma_f32_16x16x32_bf16 v[94:97], v[160:163], v[224:227], v[94:97]
	v_mfma_f32_16x16x32_bf16 v[90:93], v[168:171], v[224:227], v[90:93]
	v_mfma_f32_16x16x32_bf16 v[78:81], v[160:163], v[232:235], v[78:81]
	v_mfma_f32_16x16x32_bf16 v[74:77], v[168:171], v[232:235], v[74:77]
	s_setprio 0
	s_setprio 1
	v_mfma_f32_16x16x32_bf16 v[126:129], v[164:167], v[212:215], v[126:129]
	v_mfma_f32_16x16x32_bf16 v[122:125], v[172:175], v[212:215], v[122:125]
	v_mfma_f32_16x16x32_bf16 v[110:113], v[164:167], v[220:223], v[110:113]
	v_mfma_f32_16x16x32_bf16 v[106:109], v[172:175], v[220:223], v[106:109]
	v_mfma_f32_16x16x32_bf16 v[94:97], v[164:167], v[228:231], v[94:97]
	v_mfma_f32_16x16x32_bf16 v[90:93], v[172:175], v[228:231], v[90:93]
	v_mfma_f32_16x16x32_bf16 v[78:81], v[164:167], v[236:239], v[78:81]
	v_mfma_f32_16x16x32_bf16 v[74:77], v[172:175], v[236:239], v[74:77]
	s_setprio 0
	s_setprio 1
	v_mfma_f32_16x16x32_bf16 v[118:121], v[176:179], v[208:211], v[118:121]
	v_mfma_f32_16x16x32_bf16 v[114:117], v[184:187], v[208:211], v[114:117]
	v_mfma_f32_16x16x32_bf16 v[102:105], v[176:179], v[216:219], v[102:105]
	v_mfma_f32_16x16x32_bf16 v[98:101], v[184:187], v[216:219], v[98:101]
	v_mfma_f32_16x16x32_bf16 v[86:89], v[176:179], v[224:227], v[86:89]
	v_mfma_f32_16x16x32_bf16 v[82:85], v[184:187], v[224:227], v[82:85]
	v_mfma_f32_16x16x32_bf16 v[70:73], v[176:179], v[232:235], v[70:73]
	v_mfma_f32_16x16x32_bf16 v[66:69], v[184:187], v[232:235], v[66:69]
	s_setprio 0
	s_setprio 1
	v_mfma_f32_16x16x32_bf16 v[118:121], v[180:183], v[212:215], v[118:121]
	v_mfma_f32_16x16x32_bf16 v[114:117], v[204:207], v[212:215], v[114:117]
	v_mfma_f32_16x16x32_bf16 v[102:105], v[180:183], v[220:223], v[102:105]
	v_mfma_f32_16x16x32_bf16 v[98:101], v[204:207], v[220:223], v[98:101]
	v_mfma_f32_16x16x32_bf16 v[86:89], v[180:183], v[228:231], v[86:89]
	v_mfma_f32_16x16x32_bf16 v[82:85], v[204:207], v[228:231], v[82:85]
	v_mfma_f32_16x16x32_bf16 v[70:73], v[180:183], v[236:239], v[70:73]
	v_mfma_f32_16x16x32_bf16 v[66:69], v[204:207], v[236:239], v[66:69]
	s_setprio 0
	s_barrier
	s_add_i32 s46, s46, s4
	v_lshl_add_u64 v[240:241], s[18:19], 0, v[148:149]
	s_mov_b32 m0, s46
	ds_read_b128 v[208:211], v143 offset:16384
	ds_read_b128 v[212:215], v143 offset:17408
	ds_read_b128 v[216:219], v143 offset:18432
	ds_read_b128 v[220:223], v143 offset:19456
	ds_read_b128 v[224:227], v143 offset:20480
	ds_read_b128 v[228:231], v143 offset:21504
	ds_read_b128 v[232:235], v143 offset:22528
	ds_read_b128 v[236:239], v143 offset:23552
	global_load_lds_dwordx4 v[240:241], off
	s_add_i32 m0, s46, 0x2000
	s_add_u32 s46, s18, 0x20000
	v_lshl_add_u64 v[242:243], s[18:19], 0, v[144:145]
	s_addc_u32 s47, s19, 0
	s_add_i32 s76, s76, s4
	global_load_lds_dwordx4 v[242:243], off
	v_lshl_add_u64 v[244:245], s[46:47], 0, v[148:149]
	s_mov_b32 m0, s76
	v_lshl_add_u64 v[246:247], s[62:63], 0, v[146:147]
	global_load_lds_dwordx4 v[244:245], off
	v_lshl_add_u64 v[244:245], s[46:47], 0, v[144:145]
	s_add_i32 m0, s76, 0x2000
	s_nop 0
	global_load_lds_dwordx4 v[244:245], off
	v_lshl_add_u64 v[244:245], s[62:63], 0, v[150:151]
	s_mov_b32 m0, s5
	s_nop 0
	global_load_lds_dwordx4 v[244:245], off
	s_mov_b32 m0, s28
	s_nop 0
	global_load_lds_dwordx4 v[246:247], off
	s_waitcnt vmcnt(8)
	s_waitcnt lgkmcnt(0)
	s_barrier
; #define PG8_STAGE(bufoff, gbase, voff) do { _Pragma("unroll") for (int _i = 0; _i < 2; ++_i) \
;         __builtin_amdgcn_global_load_lds((const unsigned*)((const char*)(gbase) + (voff)[_i]), (PG8_LAS unsigned*)(lds + (bufoff) + ldsw + _i * 8192), 16, 0, 0); } while (0)
; #define PG8_LDA(dst, b, h) do { _Pragma("unroll") for (int m = 0; m < 4; ++m) _Pragma("unroll") for (int k = 0; k < 2; ++k) dst[m][k] = *(const PG8_LAS bf16x8*)(lds + PG8_SA(b, h) + aoff + m * 2048 + k * 1024); } while (0)
; #define PG8_LDB(dst, b, h) do { _Pragma("unroll") for (int n = 0; n < 2; ++n) _Pragma("unroll") for (int k = 0; k < 2; ++k) dst[n][k] = *(const PG8_LAS bf16x8*)(lds + PG8_SB(b, h) + boff + n * 2048 + k * 1024); } while (0)
; #define PG8_MMA(ai, bj, At, Bt) do { __builtin_amdgcn_s_setprio(1); _Pragma("unroll") for (int m = 0; m < 4; ++m) _Pragma("unroll") for (int n = 0; n < 2; ++n) _Pragma("unroll") for (int k = 0; k < 2; ++k) \
;         acc[ai][bj][m][n] = __builtin_amdgcn_mfma_f32_16x16x32_bf16(Bt[n][k], At[m][k], acc[ai][bj][m][n], 0, 0, 0); __builtin_amdgcn_s_setprio(0); } while (0)
; #define PG8_WAIT_V(n) asm volatile("s_waitcnt vmcnt(" #n ")" ::: "memory")
; #define PG8_WAIT_L(n) asm volatile("s_waitcnt lgkmcnt(" #n ")" ::: "memory")
; #define PG8_BAR __builtin_amdgcn_s_barrier()
; #define PG8_SCHED __builtin_amdgcn_sched_barrier(0)
; template <class Epi, class Sched, bool ALIGN_EPI = false, bool SP2 = false>
; __device__ __forceinline__ void gemm_phase(PG8_LAS unsigned char* lds, const Gemm g, const Sched& S, const Epi& E) {
;     ...
;             PG8_WAIT_V(8); PG8_WAIT_L(0); PG8_BAR; PG8_MMA(1, 0, At, B0); PG8_MMA(1, 1, At, B1); PG8_BAR; PG8_SCHED;
;             PG8_LDB(B0, 1, 0); PG8_LDB(B1, 1, 1); PG8_SCHED; PG8_LDA(At, 1, 0); PG8_STAGE(PG8_SA(0, 1), a2 + hstep, voffA);
;             PG8_WAIT_V(8); PG8_WAIT_L(0); PG8_BAR; PG8_MMA(0, 0, At, B0); PG8_MMA(0, 1, At, B1); PG8_BAR; PG8_SCHED;
	s_setprio 1
	v_mfma_f32_16x16x32_bf16 v[62:65], v[160:163], v[208:211], v[62:65]
	v_mfma_f32_16x16x32_bf16 v[58:61], v[168:171], v[208:211], v[58:61]
	v_mfma_f32_16x16x32_bf16 v[46:49], v[160:163], v[216:219], v[46:49]
	v_mfma_f32_16x16x32_bf16 v[42:45], v[168:171], v[216:219], v[42:45]
	v_mfma_f32_16x16x32_bf16 v[30:33], v[160:163], v[224:227], v[30:33]
	v_mfma_f32_16x16x32_bf16 v[26:29], v[168:171], v[224:227], v[26:29]
	v_mfma_f32_16x16x32_bf16 v[14:17], v[160:163], v[232:235], v[14:17]
	v_mfma_f32_16x16x32_bf16 v[10:13], v[168:171], v[232:235], v[10:13]
	s_setprio 0
	s_setprio 1
	v_mfma_f32_16x16x32_bf16 v[62:65], v[164:167], v[212:215], v[62:65]
	v_mfma_f32_16x16x32_bf16 v[58:61], v[172:175], v[212:215], v[58:61]
	v_mfma_f32_16x16x32_bf16 v[46:49], v[164:167], v[220:223], v[46:49]
	v_mfma_f32_16x16x32_bf16 v[42:45], v[172:175], v[220:223], v[42:45]
	v_mfma_f32_16x16x32_bf16 v[30:33], v[164:167], v[228:231], v[30:33]
	v_mfma_f32_16x16x32_bf16 v[26:29], v[172:175], v[228:231], v[26:29]
	v_mfma_f32_16x16x32_bf16 v[14:17], v[164:167], v[236:239], v[14:17]
	v_mfma_f32_16x16x32_bf16 v[10:13], v[172:175], v[236:239], v[10:13]
	s_setprio 0
	s_setprio 1
	v_mfma_f32_16x16x32_bf16 v[54:57], v[176:179], v[208:211], v[54:57]
	v_mfma_f32_16x16x32_bf16 v[50:53], v[184:187], v[208:211], v[50:53]
	v_mfma_f32_16x16x32_bf16 v[38:41], v[176:179], v[216:219], v[38:41]
	v_mfma_f32_16x16x32_bf16 v[34:37], v[184:187], v[216:219], v[34:37]
	v_mfma_f32_16x16x32_bf16 v[22:25], v[176:179], v[224:227], v[22:25]
	v_mfma_f32_16x16x32_bf16 v[18:21], v[184:187], v[224:227], v[18:21]
	v_mfma_f32_16x16x32_bf16 v[6:9], v[176:179], v[232:235], v[6:9]
	v_mfma_f32_16x16x32_bf16 v[2:5], v[184:187], v[232:235], v[2:5]
	s_setprio 0
	s_setprio 1
	v_mfma_f32_16x16x32_bf16 v[54:57], v[180:183], v[212:215], v[54:57]
	v_mfma_f32_16x16x32_bf16 v[50:53], v[204:207], v[212:215], v[50:53]
	v_mfma_f32_16x16x32_bf16 v[38:41], v[180:183], v[220:223], v[38:41]
	v_mfma_f32_16x16x32_bf16 v[34:37], v[204:207], v[220:223], v[34:37]
	v_mfma_f32_16x16x32_bf16 v[22:25], v[180:183], v[228:231], v[22:25]
	v_mfma_f32_16x16x32_bf16 v[18:21], v[204:207], v[228:231], v[18:21]
	v_mfma_f32_16x16x32_bf16 v[6:9], v[180:183], v[236:239], v[6:9]
	v_mfma_f32_16x16x32_bf16 v[2:5], v[204:207], v[236:239], v[2:5]
	s_setprio 0
	s_barrier
	s_add_i32 s76, 0, 0x18000
	s_add_i32 s77, 0, 0x1c000
	v_add_u32_e32 v172, s76, v1
	v_add_u32_e32 v203, s77, v1
	ds_read_b128 v[160:163], v172
	ds_read_b128 v[164:167], v172 offset:1024
	ds_read_b128 v[168:171], v172 offset:2048
	ds_read_b128 v[172:175], v172 offset:3072
	ds_read_b128 v[176:179], v203
	ds_read_b128 v[180:183], v203 offset:1024
	ds_read_b128 v[184:187], v203 offset:2048
	ds_read_b128 v[204:207], v203 offset:3072
	s_add_u32 s46, s62, 0x20000
	s_addc_u32 s47, s63, 0
	s_mov_b32 m0, s30
	v_lshl_add_u64 v[248:249], s[46:47], 0, v[150:151]
	ds_read_b128 v[208:211], v143 offset:32768
	ds_read_b128 v[212:215], v143 offset:33792
	ds_read_b128 v[216:219], v143 offset:34816
	ds_read_b128 v[220:223], v143 offset:35840
	ds_read_b128 v[224:227], v143 offset:36864
	ds_read_b128 v[228:231], v143 offset:37888
	ds_read_b128 v[232:235], v143 offset:38912
	ds_read_b128 v[236:239], v143 offset:39936
	global_load_lds_dwordx4 v[248:249], off
	v_lshl_add_u64 v[248:249], s[46:47], 0, v[146:147]
	s_mov_b32 m0, s34
	s_nop 0
	global_load_lds_dwordx4 v[248:249], off
	s_waitcnt vmcnt(8)
	s_waitcnt lgkmcnt(0)
	s_barrier
	s_setprio 1
	v_mfma_f32_16x16x32_bf16 v[126:129], v[160:163], v[208:211], v[126:129]
	v_mfma_f32_16x16x32_bf16 v[122:125], v[168:171], v[208:211], v[122:125]
	v_mfma_f32_16x16x32_bf16 v[110:113], v[160:163], v[216:219], v[110:113]
	v_mfma_f32_16x16x32_bf16 v[106:109], v[168:171], v[216:219], v[106:109]
	v_mfma_f32_16x16x32_bf16 v[94:97], v[160:163], v[224:227], v[94:97]
	v_mfma_f32_16x16x32_bf16 v[90:93], v[168:171], v[224:227], v[90:93]
	v_mfma_f32_16x16x32_bf16 v[78:81], v[160:163], v[232:235], v[78:81]
	v_mfma_f32_16x16x32_bf16 v[74:77], v[168:171], v[232:235], v[74:77]
	s_setprio 0
	s_setprio 1
	v_mfma_f32_16x16x32_bf16 v[126:129], v[164:167], v[212:215], v[126:129]
	v_mfma_f32_16x16x32_bf16 v[122:125], v[172:175], v[212:215], v[122:125]
	v_mfma_f32_16x16x32_bf16 v[110:113], v[164:167], v[220:223], v[110:113]
	v_mfma_f32_16x16x32_bf16 v[106:109], v[172:175], v[220:223], v[106:109]
	v_mfma_f32_16x16x32_bf16 v[94:97], v[164:167], v[228:231], v[94:97]
	v_mfma_f32_16x16x32_bf16 v[90:93], v[172:175], v[228:231], v[90:93]
	v_mfma_f32_16x16x32_bf16 v[78:81], v[164:167], v[236:239], v[78:81]
	v_mfma_f32_16x16x32_bf16 v[74:77], v[172:175], v[236:239], v[74:77]
	s_setprio 0
	s_setprio 1
	v_mfma_f32_16x16x32_bf16 v[118:121], v[176:179], v[208:211], v[118:121]
	v_mfma_f32_16x16x32_bf16 v[114:117], v[184:187], v[208:211], v[114:117]
	v_mfma_f32_16x16x32_bf16 v[102:105], v[176:179], v[216:219], v[102:105]
	v_mfma_f32_16x16x32_bf16 v[98:101], v[184:187], v[216:219], v[98:101]
	v_mfma_f32_16x16x32_bf16 v[86:89], v[176:179], v[224:227], v[86:89]
	v_mfma_f32_16x16x32_bf16 v[82:85], v[184:187], v[224:227], v[82:85]
	v_mfma_f32_16x16x32_bf16 v[70:73], v[176:179], v[232:235], v[70:73]
	v_mfma_f32_16x16x32_bf16 v[66:69], v[184:187], v[232:235], v[66:69]
	s_setprio 0
	s_setprio 1
	v_mfma_f32_16x16x32_bf16 v[118:121], v[180:183], v[212:215], v[118:121]
	v_mfma_f32_16x16x32_bf16 v[114:117], v[204:207], v[212:215], v[114:117]
	v_mfma_f32_16x16x32_bf16 v[102:105], v[180:183], v[220:223], v[102:105]
	v_mfma_f32_16x16x32_bf16 v[98:101], v[204:207], v[220:223], v[98:101]
	v_mfma_f32_16x16x32_bf16 v[86:89], v[180:183], v[228:231], v[86:89]
	v_mfma_f32_16x16x32_bf16 v[82:85], v[204:207], v[228:231], v[82:85]
	v_mfma_f32_16x16x32_bf16 v[70:73], v[180:183], v[236:239], v[70:73]
	v_mfma_f32_16x16x32_bf16 v[66:69], v[204:207], v[236:239], v[66:69]
	s_setprio 0
	s_barrier
; #define PG8_STAGE(bufoff, gbase, voff) do { _Pragma("unroll") for (int _i = 0; _i < 2; ++_i) \
;         __builtin_amdgcn_global_load_lds((const unsigned*)((const char*)(gbase) + (voff)[_i]), (PG8_LAS unsigned*)(lds + (bufoff) + ldsw + _i * 8192), 16, 0, 0); } while (0)
; #define PG8_LDA(dst, b, h) do { _Pragma("unroll") for (int m = 0; m < 4; ++m) _Pragma("unroll") for (int k = 0; k < 2; ++k) dst[m][k] = *(const PG8_LAS bf16x8*)(lds + PG8_SA(b, h) + aoff + m * 2048 + k * 1024); } while (0)
; #define PG8_MMA(ai, bj, At, Bt) do { __builtin_amdgcn_s_setprio(1); _Pragma("unroll") for (int m = 0; m < 4; ++m) _Pragma("unroll") for (int n = 0; n < 2; ++n) _Pragma("unroll") for (int k = 0; k < 2; ++k) \
;         acc[ai][bj][m][n] = __builtin_amdgcn_mfma_f32_16x16x32_bf16(Bt[n][k], At[m][k], acc[ai][bj][m][n], 0, 0, 0); __builtin_amdgcn_s_setprio(0); } while (0)
; #define PG8_WAIT_V(n) asm volatile("s_waitcnt vmcnt(" #n ")" ::: "memory")
; #define PG8_WAIT_L(n) asm volatile("s_waitcnt lgkmcnt(" #n ")" ::: "memory")
; #define PG8_BAR __builtin_amdgcn_s_barrier()
; #define PG8_SCHED __builtin_amdgcn_sched_barrier(0)
;     __device__ __forceinline__ void operator()(const f32x4 (&acc)[2][2][4][2], const Unit& u, int wr, int wc, int fr, int fq) const {
;     ...
;         const u32x4* gp = (const u32x4*)G8 + (size_t)(u.pm * 16 + gsel + u.pn) * 8 * 512 + tidn;
;         u32x4* mp = M1 + (size_t)(u.pm * 8 + u.pn) * 16 * 512 + tidn;
;         constexpr float K255 = 1.0f / 255.0f;
; #pragma unroll
;         for (int ai = 0; ai < 2; ++ai)
; #pragma unroll
;             for (int m = 0; m < 4; ++m) { const size_t row = (size_t)(row0 + ai * HALF + m * 16);
;                 const u32x4 gw = gp[(ai * 4 + m) * 512];
; template <class Epi, class Sched, bool ALIGN_EPI = false, bool SP2 = false>
; __device__ __forceinline__ void gemm_phase(PG8_LAS unsigned char* lds, const Gemm g, const Sched& S, const Epi& E) {
;     ...
;             PG8_LDA(At, 1, 1); PG8_STAGE(PG8_SB(1, 0), b3, voffB); PG8_STAGE(PG8_SB(1, 1), b3 + hstep, voffB); PG8_STAGE(PG8_SA(1, 0), a3, voffA);
;             PG8_WAIT_V(8); PG8_WAIT_L(0); PG8_BAR; PG8_MMA(1, 0, At, B0); PG8_MMA(1, 1, At, B1); PG8_BAR; PG8_SCHED;
;     ...
;         if constexpr (ALIGN_EPI) { if (wr == 0) PG8_BAR; }
	s_add_i32 s46, s76, s4
	v_lshl_add_u64 v[240:241], v[240:241], 0, s[68:69]
	s_mov_b32 m0, s46
	ds_read_b128 v[208:211], v143 offset:49152
	ds_read_b128 v[212:215], v143 offset:50176
	ds_read_b128 v[216:219], v143 offset:51200
	ds_read_b128 v[220:223], v143 offset:52224
	ds_read_b128 v[224:227], v143 offset:53248
	ds_read_b128 v[228:231], v143 offset:54272
	ds_read_b128 v[232:235], v143 offset:55296
	ds_read_b128 v[236:239], v143 offset:56320
	global_load_lds_dwordx4 v[240:241], off
	s_add_i32 m0, s46, 0x2000
	s_add_u32 s18, s18, 0x20080
	v_lshl_add_u64 v[240:241], v[242:243], 0, s[68:69]
	s_addc_u32 s19, s19, 0
	s_add_i32 s46, s77, s4
	global_load_lds_dwordx4 v[240:241], off
	v_lshl_add_u64 v[240:241], s[18:19], 0, v[148:149]
	s_mov_b32 m0, s46
	s_nop 0
	global_load_lds_dwordx4 v[240:241], off
	v_lshl_add_u64 v[240:241], s[18:19], 0, v[144:145]
	s_add_i32 m0, s46, 0x2000
	s_nop 0
	global_load_lds_dwordx4 v[240:241], off
	v_lshl_add_u64 v[240:241], v[244:245], 0, s[68:69]
	s_mov_b32 m0, s54
	s_nop 0
	global_load_lds_dwordx4 v[240:241], off
	v_lshl_add_u64 v[240:241], v[246:247], 0, s[68:69]
	s_mov_b32 m0, s57
	s_nop 0
	global_load_lds_dwordx4 v[240:241], off
	s_waitcnt vmcnt(8)
	s_waitcnt lgkmcnt(0)
	s_barrier
	s_setprio 1
	v_mfma_f32_16x16x32_bf16 v[62:65], v[160:163], v[208:211], v[62:65]
	v_mfma_f32_16x16x32_bf16 v[58:61], v[168:171], v[208:211], v[58:61]
	v_mfma_f32_16x16x32_bf16 v[46:49], v[160:163], v[216:219], v[46:49]
	v_mfma_f32_16x16x32_bf16 v[42:45], v[168:171], v[216:219], v[42:45]
	v_mfma_f32_16x16x32_bf16 v[30:33], v[160:163], v[224:227], v[30:33]
	v_mfma_f32_16x16x32_bf16 v[26:29], v[168:171], v[224:227], v[26:29]
	v_mfma_f32_16x16x32_bf16 v[14:17], v[160:163], v[232:235], v[14:17]
	v_mfma_f32_16x16x32_bf16 v[10:13], v[168:171], v[232:235], v[10:13]
	s_setprio 0
	s_setprio 1
	v_mfma_f32_16x16x32_bf16 v[62:65], v[164:167], v[212:215], v[62:65]
	v_mfma_f32_16x16x32_bf16 v[58:61], v[172:175], v[212:215], v[58:61]
	v_mfma_f32_16x16x32_bf16 v[46:49], v[164:167], v[220:223], v[46:49]
	v_mfma_f32_16x16x32_bf16 v[42:45], v[172:175], v[220:223], v[42:45]
	v_mfma_f32_16x16x32_bf16 v[30:33], v[164:167], v[228:231], v[30:33]
	v_mfma_f32_16x16x32_bf16 v[26:29], v[172:175], v[228:231], v[26:29]
	v_mfma_f32_16x16x32_bf16 v[14:17], v[164:167], v[236:239], v[14:17]
	v_mfma_f32_16x16x32_bf16 v[10:13], v[172:175], v[236:239], v[10:13]
	s_setprio 0
	s_setprio 1
	v_mfma_f32_16x16x32_bf16 v[54:57], v[176:179], v[208:211], v[54:57]
	v_mfma_f32_16x16x32_bf16 v[50:53], v[184:187], v[208:211], v[50:53]
	v_mfma_f32_16x16x32_bf16 v[38:41], v[176:179], v[216:219], v[38:41]
	v_mfma_f32_16x16x32_bf16 v[34:37], v[184:187], v[216:219], v[34:37]
	v_mfma_f32_16x16x32_bf16 v[22:25], v[176:179], v[224:227], v[22:25]
	v_mfma_f32_16x16x32_bf16 v[18:21], v[184:187], v[224:227], v[18:21]
	v_mfma_f32_16x16x32_bf16 v[6:9], v[176:179], v[232:235], v[6:9]
	v_mfma_f32_16x16x32_bf16 v[2:5], v[184:187], v[232:235], v[2:5]
	s_setprio 0
	s_setprio 1
	v_mfma_f32_16x16x32_bf16 v[54:57], v[180:183], v[212:215], v[54:57]
	v_mfma_f32_16x16x32_bf16 v[50:53], v[204:207], v[212:215], v[50:53]
	v_mfma_f32_16x16x32_bf16 v[38:41], v[180:183], v[220:223], v[38:41]
	v_mfma_f32_16x16x32_bf16 v[34:37], v[204:207], v[220:223], v[34:37]
	v_mfma_f32_16x16x32_bf16 v[22:25], v[180:183], v[228:231], v[22:25]
	v_mfma_f32_16x16x32_bf16 v[18:21], v[204:207], v[228:231], v[18:21]
	v_mfma_f32_16x16x32_bf16 v[6:9], v[180:183], v[236:239], v[6:9]
	v_mfma_f32_16x16x32_bf16 v[2:5], v[204:207], v[236:239], v[2:5]
	s_setprio 0
	s_barrier
	s_add_i32 s79, s79, 2
	s_add_u32 s58, s58, 0x100
	s_addc_u32 s59, s59, 0
	s_add_u32 s85, s85, 0x100
	s_addc_u32 s78, s78, 0
	s_cmp_gt_u32 s79, 5
	s_cbranch_scc0 .LBB0_136
	s_lshl_b32 s11, s67, 4
	s_add_i32 s18, s11, s86
	s_ashr_i32 s19, s18, 31
	s_lshl_b64 s[46:47], s[18:19], 16
	v_lshl_add_u64 v[162:163], v[152:153], 0, s[46:47]
	s_lshl_b32 s11, s67, 3
	s_sub_i32 s18, s18, s11
	s_ashr_i32 s19, s18, 31
	s_lshl_b64 s[18:19], s[18:19], 17
	v_lshl_add_u64 v[160:161], v[154:155], 0, s[18:19]
	s_mov_b32 s47, 0
	global_load_dwordx4 v[168:171], v[162:163], off
	s_mov_b32 s46, 0x2000
	v_lshl_add_u64 v[164:165], v[162:163], 0, s[46:47]
	global_load_dwordx4 v[172:175], v[164:165], off
	s_mov_b32 s46, 0x4000
	v_lshl_add_u64 v[164:165], v[162:163], 0, s[46:47]
	global_load_dwordx4 v[176:179], v[164:165], off
	s_mov_b32 s46, 0x6000
	v_lshl_add_u64 v[164:165], v[162:163], 0, s[46:47]
	global_load_dwordx4 v[180:183], v[164:165], off
	s_mov_b32 s46, 0x8000
	v_lshl_add_u64 v[164:165], v[162:163], 0, s[46:47]
	global_load_dwordx4 v[184:187], v[164:165], off
	s_mov_b32 s46, 0xa000
	v_lshl_add_u64 v[164:165], v[162:163], 0, s[46:47]
	global_load_dwordx4 v[204:207], v[164:165], off
	s_mov_b32 s46, 0xc000
	v_lshl_add_u64 v[164:165], v[162:163], 0, s[46:47]
	global_load_dwordx4 v[208:211], v[164:165], off
	s_mov_b32 s46, 0xe000
	v_lshl_add_u64 v[164:165], v[162:163], 0, s[46:47]
	global_load_dwordx4 v[212:215], v[164:165], off
	s_and_b64 vcc, exec, s[8:9]
	s_cbranch_vccz .Lg0_nobar
	s_barrier

; #define PG8_STAGE(bufoff, gbase, voff) do { _Pragma("unroll") for (int _i = 0; _i < 2; ++_i) \
;         __builtin_amdgcn_global_load_lds((const unsigned*)((const char*)(gbase) + (voff)[_i]), (PG8_LAS unsigned*)(lds + (bufoff) + ldsw + _i * 8192), 16, 0, 0); } while (0)
; #define PG8_LDA(dst, b, h) do { _Pragma("unroll") for (int m = 0; m < 4; ++m) _Pragma("unroll") for (int k = 0; k < 2; ++k) dst[m][k] = *(const PG8_LAS bf16x8*)(lds + PG8_SA(b, h) + aoff + m * 2048 + k * 1024); } while (0)
; #define PG8_LDB(dst, b, h) do { _Pragma("unroll") for (int n = 0; n < 2; ++n) _Pragma("unroll") for (int k = 0; k < 2; ++k) dst[n][k] = *(const PG8_LAS bf16x8*)(lds + PG8_SB(b, h) + boff + n * 2048 + k * 1024); } while (0)
; #define PG8_WAIT_V(n) asm volatile("s_waitcnt vmcnt(" #n ")" ::: "memory")
; #define PG8_WAIT_L(n) asm volatile("s_waitcnt lgkmcnt(" #n ")" ::: "memory")
; #define PG8_BAR __builtin_amdgcn_s_barrier()
; #define PG8_SCHED __builtin_amdgcn_sched_barrier(0)
; template <class Epi, class Sched, bool ALIGN_EPI = false, bool SP2 = false>
; __device__ __forceinline__ void gemm_phase(PG8_LAS unsigned char* lds, const Gemm g, const Sched& S, const Epi& E) {
;     ...
;         const char* nA = has_next ? (const char*)g.A + (size_t)nxt.pm * tstep : cA; const char* nB = has_next ? (const char*)g.Bt + (size_t)nxt.pn * tstep : cB;
;         for (int t = 0; t < nt; t += 2) {
;             const bool last = (t == nt - 2);
;             const char* a1 = cA + (size_t)(t + 1) * kstep;
;             const char* a2 = last ? nA : cA + (size_t)(t + 2) * kstep; const char* b2 = last ? nB : cB + (size_t)(t + 2) * kstep;
;             const char* a3 = a2 + kstep; const char* b3 = b2 + kstep;
;             if (last && has_next) S.a_ready(nxt);
;             if constexpr (SP2) {
;             PG8_LDB(B0, 0, 0); PG8_LDB(B1, 0, 1); PG8_SCHED; PG8_LDA(At, 0, 0); PG8_STAGE(PG8_SA(1, 1), a1 + hstep, voffA);
;             PG8_WAIT_V(8); PG8_WAIT_L(0); PG8_BAR; PG8_MMA(0, 0, At, B0); PG8_MMA(0, 1, At, B1); PG8_BAR; PG8_SCHED;
;             PG8_LDA(At, 0, 1); PG8_STAGE(PG8_SB(0, 0), b2, voffB); PG8_STAGE(PG8_SB(0, 1), b2 + hstep, voffB); PG8_STAGE(PG8_SA(0, 0), a2, voffA);
;             PG8_WAIT_V(8); PG8_WAIT_L(0); PG8_BAR; PG8_MMA(1, 0, At, B0); PG8_MMA(1, 1, At, B1); PG8_BAR; PG8_SCHED;
.LBB0_160:
	s_add_u32 s42, s36, 0x100
	s_addc_u32 s43, s37, 0
	s_add_i32 s47, 0, 0x10000
	s_cmp_eq_u32 s46, 20
	s_cselect_b32 s45, s1, s43
	s_cselect_b32 s44, s0, s42
	s_cselect_b32 s19, s7, s73
	s_cselect_b32 s18, s6, s60
	s_add_i32 s76, 0, 0x14000
	v_add_u32_e32 v174, s47, v143
	v_add_u32_e32 v186, s76, v143
	ds_read_b128 v[160:163], v174
	ds_read_b128 v[164:167], v174 offset:1024
	ds_read_b128 v[170:173], v174 offset:2048
	ds_read_b128 v[174:177], v174 offset:3072
	ds_read_b128 v[178:181], v186
	ds_read_b128 v[182:185], v186 offset:1024
	ds_read_b128 v[204:207], v186 offset:2048
	ds_read_b128 v[208:211], v186 offset:3072
	v_lshl_add_u64 v[186:187], s[36:37], 0, v[156:157]
	s_add_i32 m0, s54, 0xc000
	ds_read_b128 v[212:215], v169
	ds_read_b128 v[216:219], v169 offset:1024
	ds_read_b128 v[220:223], v169 offset:2048
	ds_read_b128 v[224:227], v169 offset:3072
	ds_read_b128 v[228:231], v169 offset:4096
	ds_read_b128 v[232:235], v169 offset:5120
	ds_read_b128 v[236:239], v169 offset:6144
	ds_read_b128 v[240:243], v169 offset:7168
	global_load_lds_dwordx4 v[186:187], off
	v_lshl_add_u64 v[186:187], s[36:37], 0, v[158:159]
	s_add_i32 m0, s54, 0xe000
	s_nop 0
	global_load_lds_dwordx4 v[186:187], off
	s_waitcnt vmcnt(8)
	s_waitcnt lgkmcnt(0)
	s_barrier
	s_setprio 1
	v_mfma_f32_16x16x32_bf16 v[126:129], v[160:163], v[212:215], v[126:129]
	v_mfma_f32_16x16x32_bf16 v[122:125], v[170:173], v[212:215], v[122:125]
	v_mfma_f32_16x16x32_bf16 v[110:113], v[160:163], v[220:223], v[110:113]
	v_mfma_f32_16x16x32_bf16 v[106:109], v[170:173], v[220:223], v[106:109]
	v_mfma_f32_16x16x32_bf16 v[94:97], v[160:163], v[228:231], v[94:97]
	v_mfma_f32_16x16x32_bf16 v[90:93], v[170:173], v[228:231], v[90:93]
	v_mfma_f32_16x16x32_bf16 v[78:81], v[160:163], v[236:239], v[78:81]
	v_mfma_f32_16x16x32_bf16 v[74:77], v[170:173], v[236:239], v[74:77]
	s_setprio 0
	s_setprio 1
	v_mfma_f32_16x16x32_bf16 v[126:129], v[164:167], v[216:219], v[126:129]
	v_mfma_f32_16x16x32_bf16 v[122:125], v[174:177], v[216:219], v[122:125]
	v_mfma_f32_16x16x32_bf16 v[110:113], v[164:167], v[224:227], v[110:113]
	v_mfma_f32_16x16x32_bf16 v[106:109], v[174:177], v[224:227], v[106:109]
	v_mfma_f32_16x16x32_bf16 v[94:97], v[164:167], v[232:235], v[94:97]
	v_mfma_f32_16x16x32_bf16 v[90:93], v[174:177], v[232:235], v[90:93]
	v_mfma_f32_16x16x32_bf16 v[78:81], v[164:167], v[240:243], v[78:81]
	v_mfma_f32_16x16x32_bf16 v[74:77], v[174:177], v[240:243], v[74:77]
	s_setprio 0
	s_setprio 1
	v_mfma_f32_16x16x32_bf16 v[118:121], v[178:181], v[212:215], v[118:121]
	v_mfma_f32_16x16x32_bf16 v[114:117], v[204:207], v[212:215], v[114:117]
	v_mfma_f32_16x16x32_bf16 v[102:105], v[178:181], v[220:223], v[102:105]
	v_mfma_f32_16x16x32_bf16 v[98:101], v[204:207], v[220:223], v[98:101]
	v_mfma_f32_16x16x32_bf16 v[86:89], v[178:181], v[228:231], v[86:89]
	v_mfma_f32_16x16x32_bf16 v[82:85], v[204:207], v[228:231], v[82:85]
	v_mfma_f32_16x16x32_bf16 v[70:73], v[178:181], v[236:239], v[70:73]
	v_mfma_f32_16x16x32_bf16 v[66:69], v[204:207], v[236:239], v[66:69]
	s_setprio 0
	s_setprio 1
	v_mfma_f32_16x16x32_bf16 v[118:121], v[182:185], v[216:219], v[118:121]
	v_mfma_f32_16x16x32_bf16 v[114:117], v[208:211], v[216:219], v[114:117]
	v_mfma_f32_16x16x32_bf16 v[102:105], v[182:185], v[224:227], v[102:105]
	v_mfma_f32_16x16x32_bf16 v[98:101], v[208:211], v[224:227], v[98:101]
	v_mfma_f32_16x16x32_bf16 v[86:89], v[182:185], v[232:235], v[86:89]
	v_mfma_f32_16x16x32_bf16 v[82:85], v[208:211], v[232:235], v[82:85]
	v_mfma_f32_16x16x32_bf16 v[70:73], v[182:185], v[240:243], v[70:73]
	v_mfma_f32_16x16x32_bf16 v[66:69], v[208:211], v[240:243], v[66:69]
	s_setprio 0
	s_barrier
	s_add_i32 s36, s47, s4
	v_lshl_add_u64 v[186:187], s[18:19], 0, v[148:149]
	s_mov_b32 m0, s36
	ds_read_b128 v[212:215], v169 offset:16384
	ds_read_b128 v[216:219], v169 offset:17408
	ds_read_b128 v[220:223], v169 offset:18432
	ds_read_b128 v[224:227], v169 offset:19456
	ds_read_b128 v[228:231], v169 offset:20480
	ds_read_b128 v[232:235], v169 offset:21504
	ds_read_b128 v[236:239], v169 offset:22528
	ds_read_b128 v[240:243], v169 offset:23552
	global_load_lds_dwordx4 v[186:187], off
	s_add_i32 m0, s36, 0x2000
	s_add_u32 s36, s18, 0x60000
	v_lshl_add_u64 v[244:245], s[18:19], 0, v[144:145]
	s_addc_u32 s37, s19, 0
	s_add_i32 s47, s76, s4
	global_load_lds_dwordx4 v[244:245], off
	v_lshl_add_u64 v[246:247], s[36:37], 0, v[148:149]
	s_mov_b32 m0, s47
	v_lshl_add_u64 v[248:249], s[44:45], 0, v[146:147]
	global_load_lds_dwordx4 v[246:247], off
	v_lshl_add_u64 v[246:247], s[36:37], 0, v[144:145]
	s_add_i32 m0, s47, 0x2000
	s_nop 0
	global_load_lds_dwordx4 v[246:247], off
	v_lshl_add_u64 v[246:247], s[44:45], 0, v[150:151]
	s_mov_b32 m0, s54
	s_nop 0
	global_load_lds_dwordx4 v[246:247], off
	s_mov_b32 m0, s57
	s_nop 0
	global_load_lds_dwordx4 v[248:249], off
	s_waitcnt vmcnt(8)
	s_waitcnt lgkmcnt(0)
	s_barrier
; #define PG8_STAGE(bufoff, gbase, voff) do { _Pragma("unroll") for (int _i = 0; _i < 2; ++_i) \
;         __builtin_amdgcn_global_load_lds((const unsigned*)((const char*)(gbase) + (voff)[_i]), (PG8_LAS unsigned*)(lds + (bufoff) + ldsw + _i * 8192), 16, 0, 0); } while (0)
; #define PG8_LDA(dst, b, h) do { _Pragma("unroll") for (int m = 0; m < 4; ++m) _Pragma("unroll") for (int k = 0; k < 2; ++k) dst[m][k] = *(const PG8_LAS bf16x8*)(lds + PG8_SA(b, h) + aoff + m * 2048 + k * 1024); } while (0)
; #define PG8_LDB(dst, b, h) do { _Pragma("unroll") for (int n = 0; n < 2; ++n) _Pragma("unroll") for (int k = 0; k < 2; ++k) dst[n][k] = *(const PG8_LAS bf16x8*)(lds + PG8_SB(b, h) + boff + n * 2048 + k * 1024); } while (0)
; #define PG8_MMA(ai, bj, At, Bt) do { __builtin_amdgcn_s_setprio(1); _Pragma("unroll") for (int m = 0; m < 4; ++m) _Pragma("unroll") for (int n = 0; n < 2; ++n) _Pragma("unroll") for (int k = 0; k < 2; ++k) \
;         acc[ai][bj][m][n] = __builtin_amdgcn_mfma_f32_16x16x32_bf16(Bt[n][k], At[m][k], acc[ai][bj][m][n], 0, 0, 0); __builtin_amdgcn_s_setprio(0); } while (0)
; #define PG8_WAIT_V(n) asm volatile("s_waitcnt vmcnt(" #n ")" ::: "memory")
; #define PG8_WAIT_L(n) asm volatile("s_waitcnt lgkmcnt(" #n ")" ::: "memory")
; #define PG8_BAR __builtin_amdgcn_s_barrier()
; #define PG8_SCHED __builtin_amdgcn_sched_barrier(0)
; template <class Epi, class Sched, bool ALIGN_EPI = false, bool SP2 = false>
; __device__ __forceinline__ void gemm_phase(PG8_LAS unsigned char* lds, const Gemm g, const Sched& S, const Epi& E) {
;     ...
;             PG8_WAIT_V(8); PG8_WAIT_L(0); PG8_BAR; PG8_MMA(1, 0, At, B0); PG8_MMA(1, 1, At, B1); PG8_BAR; PG8_SCHED;
;             PG8_LDB(B0, 1, 0); PG8_LDB(B1, 1, 1); PG8_SCHED; PG8_LDA(At, 1, 0); PG8_STAGE(PG8_SA(0, 1), a2 + hstep, voffA);
;             PG8_WAIT_V(8); PG8_WAIT_L(0); PG8_BAR; PG8_MMA(0, 0, At, B0); PG8_MMA(0, 1, At, B1); PG8_BAR; PG8_SCHED;
	s_setprio 1
	v_mfma_f32_16x16x32_bf16 v[62:65], v[160:163], v[212:215], v[62:65]
	v_mfma_f32_16x16x32_bf16 v[58:61], v[170:173], v[212:215], v[58:61]
	v_mfma_f32_16x16x32_bf16 v[46:49], v[160:163], v[220:223], v[46:49]
	v_mfma_f32_16x16x32_bf16 v[42:45], v[170:173], v[220:223], v[42:45]
	v_mfma_f32_16x16x32_bf16 v[30:33], v[160:163], v[228:231], v[30:33]
	v_mfma_f32_16x16x32_bf16 v[26:29], v[170:173], v[228:231], v[26:29]
	v_mfma_f32_16x16x32_bf16 v[14:17], v[160:163], v[236:239], v[14:17]
	v_mfma_f32_16x16x32_bf16 v[10:13], v[170:173], v[236:239], v[10:13]
	s_setprio 0
	s_setprio 1
	v_mfma_f32_16x16x32_bf16 v[62:65], v[164:167], v[216:219], v[62:65]
	v_mfma_f32_16x16x32_bf16 v[58:61], v[174:177], v[216:219], v[58:61]
	v_mfma_f32_16x16x32_bf16 v[46:49], v[164:167], v[224:227], v[46:49]
	v_mfma_f32_16x16x32_bf16 v[42:45], v[174:177], v[224:227], v[42:45]
	v_mfma_f32_16x16x32_bf16 v[30:33], v[164:167], v[232:235], v[30:33]
	v_mfma_f32_16x16x32_bf16 v[26:29], v[174:177], v[232:235], v[26:29]
	v_mfma_f32_16x16x32_bf16 v[14:17], v[164:167], v[240:243], v[14:17]
	v_mfma_f32_16x16x32_bf16 v[10:13], v[174:177], v[240:243], v[10:13]
	s_setprio 0
	s_setprio 1
	v_mfma_f32_16x16x32_bf16 v[54:57], v[178:181], v[212:215], v[54:57]
	v_mfma_f32_16x16x32_bf16 v[50:53], v[204:207], v[212:215], v[50:53]
	v_mfma_f32_16x16x32_bf16 v[38:41], v[178:181], v[220:223], v[38:41]
	v_mfma_f32_16x16x32_bf16 v[34:37], v[204:207], v[220:223], v[34:37]
	v_mfma_f32_16x16x32_bf16 v[22:25], v[178:181], v[228:231], v[22:25]
	v_mfma_f32_16x16x32_bf16 v[18:21], v[204:207], v[228:231], v[18:21]
	v_mfma_f32_16x16x32_bf16 v[6:9], v[178:181], v[236:239], v[6:9]
	v_mfma_f32_16x16x32_bf16 v[2:5], v[204:207], v[236:239], v[2:5]
	s_setprio 0
	s_setprio 1
	v_mfma_f32_16x16x32_bf16 v[54:57], v[182:185], v[216:219], v[54:57]
	v_mfma_f32_16x16x32_bf16 v[50:53], v[208:211], v[216:219], v[50:53]
	v_mfma_f32_16x16x32_bf16 v[38:41], v[182:185], v[224:227], v[38:41]
	v_mfma_f32_16x16x32_bf16 v[34:37], v[208:211], v[224:227], v[34:37]
	v_mfma_f32_16x16x32_bf16 v[22:25], v[182:185], v[232:235], v[22:25]
	v_mfma_f32_16x16x32_bf16 v[18:21], v[208:211], v[232:235], v[18:21]
	v_mfma_f32_16x16x32_bf16 v[6:9], v[182:185], v[240:243], v[6:9]
	v_mfma_f32_16x16x32_bf16 v[2:5], v[208:211], v[240:243], v[2:5]
	s_setprio 0
	s_barrier
	s_add_i32 s47, 0, 0x18000
	s_add_i32 s76, 0, 0x1c000
	v_add_u32_e32 v174, s47, v143
	v_add_u32_e32 v203, s76, v143
	ds_read_b128 v[160:163], v174
	ds_read_b128 v[164:167], v174 offset:1024
	ds_read_b128 v[170:173], v174 offset:2048
	ds_read_b128 v[174:177], v174 offset:3072
	ds_read_b128 v[178:181], v203
	ds_read_b128 v[182:185], v203 offset:1024
	ds_read_b128 v[204:207], v203 offset:2048
	ds_read_b128 v[208:211], v203 offset:3072
	s_add_u32 s36, s44, 0x60000
	s_addc_u32 s37, s45, 0
	s_mov_b32 m0, s58
	v_lshl_add_u64 v[250:251], s[36:37], 0, v[150:151]
	ds_read_b128 v[212:215], v169 offset:32768
	ds_read_b128 v[216:219], v169 offset:33792
	ds_read_b128 v[220:223], v169 offset:34816
	ds_read_b128 v[224:227], v169 offset:35840
	ds_read_b128 v[228:231], v169 offset:36864
	ds_read_b128 v[232:235], v169 offset:37888
	ds_read_b128 v[236:239], v169 offset:38912
	ds_read_b128 v[240:243], v169 offset:39936
	global_load_lds_dwordx4 v[250:251], off
	v_lshl_add_u64 v[250:251], s[36:37], 0, v[146:147]
	s_mov_b32 m0, s59
	s_nop 0
	global_load_lds_dwordx4 v[250:251], off
	s_waitcnt vmcnt(8)
	s_waitcnt lgkmcnt(0)
	s_barrier
	s_setprio 1
	v_mfma_f32_16x16x32_bf16 v[126:129], v[160:163], v[212:215], v[126:129]
	v_mfma_f32_16x16x32_bf16 v[122:125], v[170:173], v[212:215], v[122:125]
	v_mfma_f32_16x16x32_bf16 v[110:113], v[160:163], v[220:223], v[110:113]
	v_mfma_f32_16x16x32_bf16 v[106:109], v[170:173], v[220:223], v[106:109]
	v_mfma_f32_16x16x32_bf16 v[94:97], v[160:163], v[228:231], v[94:97]
	v_mfma_f32_16x16x32_bf16 v[90:93], v[170:173], v[228:231], v[90:93]
	v_mfma_f32_16x16x32_bf16 v[78:81], v[160:163], v[236:239], v[78:81]
	v_mfma_f32_16x16x32_bf16 v[74:77], v[170:173], v[236:239], v[74:77]
	s_setprio 0
	s_setprio 1
	v_mfma_f32_16x16x32_bf16 v[126:129], v[164:167], v[216:219], v[126:129]
	v_mfma_f32_16x16x32_bf16 v[122:125], v[174:177], v[216:219], v[122:125]
	v_mfma_f32_16x16x32_bf16 v[110:113], v[164:167], v[224:227], v[110:113]
	v_mfma_f32_16x16x32_bf16 v[106:109], v[174:177], v[224:227], v[106:109]
	v_mfma_f32_16x16x32_bf16 v[94:97], v[164:167], v[232:235], v[94:97]
	v_mfma_f32_16x16x32_bf16 v[90:93], v[174:177], v[232:235], v[90:93]
	v_mfma_f32_16x16x32_bf16 v[78:81], v[164:167], v[240:243], v[78:81]
	v_mfma_f32_16x16x32_bf16 v[74:77], v[174:177], v[240:243], v[74:77]
	s_setprio 0
	s_setprio 1
	v_mfma_f32_16x16x32_bf16 v[118:121], v[178:181], v[212:215], v[118:121]
	v_mfma_f32_16x16x32_bf16 v[114:117], v[204:207], v[212:215], v[114:117]
	v_mfma_f32_16x16x32_bf16 v[102:105], v[178:181], v[220:223], v[102:105]
	v_mfma_f32_16x16x32_bf16 v[98:101], v[204:207], v[220:223], v[98:101]
	v_mfma_f32_16x16x32_bf16 v[86:89], v[178:181], v[228:231], v[86:89]
	v_mfma_f32_16x16x32_bf16 v[82:85], v[204:207], v[228:231], v[82:85]
	v_mfma_f32_16x16x32_bf16 v[70:73], v[178:181], v[236:239], v[70:73]
	v_mfma_f32_16x16x32_bf16 v[66:69], v[204:207], v[236:239], v[66:69]
	s_setprio 0
	s_setprio 1
	v_mfma_f32_16x16x32_bf16 v[118:121], v[182:185], v[216:219], v[118:121]
	v_mfma_f32_16x16x32_bf16 v[114:117], v[208:211], v[216:219], v[114:117]
	v_mfma_f32_16x16x32_bf16 v[102:105], v[182:185], v[224:227], v[102:105]
	v_mfma_f32_16x16x32_bf16 v[98:101], v[208:211], v[224:227], v[98:101]
	v_mfma_f32_16x16x32_bf16 v[86:89], v[182:185], v[232:235], v[86:89]
	v_mfma_f32_16x16x32_bf16 v[82:85], v[208:211], v[232:235], v[82:85]
	v_mfma_f32_16x16x32_bf16 v[70:73], v[182:185], v[240:243], v[70:73]
	v_mfma_f32_16x16x32_bf16 v[66:69], v[208:211], v[240:243], v[66:69]
	s_setprio 0
	s_barrier
; #define PG8_STAGE(bufoff, gbase, voff) do { _Pragma("unroll") for (int _i = 0; _i < 2; ++_i) \
;         __builtin_amdgcn_global_load_lds((const unsigned*)((const char*)(gbase) + (voff)[_i]), (PG8_LAS unsigned*)(lds + (bufoff) + ldsw + _i * 8192), 16, 0, 0); } while (0)
; #define PG8_LDA(dst, b, h) do { _Pragma("unroll") for (int m = 0; m < 4; ++m) _Pragma("unroll") for (int k = 0; k < 2; ++k) dst[m][k] = *(const PG8_LAS bf16x8*)(lds + PG8_SA(b, h) + aoff + m * 2048 + k * 1024); } while (0)
; #define PG8_MMA(ai, bj, At, Bt) do { __builtin_amdgcn_s_setprio(1); _Pragma("unroll") for (int m = 0; m < 4; ++m) _Pragma("unroll") for (int n = 0; n < 2; ++n) _Pragma("unroll") for (int k = 0; k < 2; ++k) \
;         acc[ai][bj][m][n] = __builtin_amdgcn_mfma_f32_16x16x32_bf16(Bt[n][k], At[m][k], acc[ai][bj][m][n], 0, 0, 0); __builtin_amdgcn_s_setprio(0); } while (0)
; #define PG8_WAIT_V(n) asm volatile("s_waitcnt vmcnt(" #n ")" ::: "memory")
; #define PG8_WAIT_L(n) asm volatile("s_waitcnt lgkmcnt(" #n ")" ::: "memory")
; #define PG8_BAR __builtin_amdgcn_s_barrier()
; #define PG8_SCHED __builtin_amdgcn_sched_barrier(0)
; template <class Epi, class Sched, bool ALIGN_EPI = false, bool SP2 = false>
; __device__ __forceinline__ void gemm_phase(PG8_LAS unsigned char* lds, const Gemm g, const Sched& S, const Epi& E) {
;     ...
;             PG8_LDA(At, 1, 1); PG8_STAGE(PG8_SB(1, 0), b3, voffB); PG8_STAGE(PG8_SB(1, 1), b3 + hstep, voffB); PG8_STAGE(PG8_SA(1, 0), a3, voffA);
;             PG8_WAIT_V(8); PG8_WAIT_L(0); PG8_BAR; PG8_MMA(1, 0, At, B0); PG8_MMA(1, 1, At, B1); PG8_BAR; PG8_SCHED;
;     ...
;         if constexpr (ALIGN_EPI) { if (wr == 0) PG8_BAR; }
	s_add_i32 s36, s47, s4
	v_lshl_add_u64 v[186:187], v[186:187], 0, s[68:69]
	s_mov_b32 m0, s36
	ds_read_b128 v[212:215], v169 offset:49152
	ds_read_b128 v[216:219], v169 offset:50176
	ds_read_b128 v[220:223], v169 offset:51200
	ds_read_b128 v[224:227], v169 offset:52224
	ds_read_b128 v[228:231], v169 offset:53248
	ds_read_b128 v[232:235], v169 offset:54272
	ds_read_b128 v[236:239], v169 offset:55296
	ds_read_b128 v[240:243], v169 offset:56320
	global_load_lds_dwordx4 v[186:187], off
	s_add_i32 m0, s36, 0x2000
	s_add_u32 s18, s18, 0x60080
	v_lshl_add_u64 v[186:187], v[244:245], 0, s[68:69]
	s_addc_u32 s19, s19, 0
	s_add_i32 s36, s76, s4
	global_load_lds_dwordx4 v[186:187], off
	v_lshl_add_u64 v[186:187], s[18:19], 0, v[148:149]
	s_mov_b32 m0, s36
	s_nop 0
	global_load_lds_dwordx4 v[186:187], off
	v_lshl_add_u64 v[186:187], s[18:19], 0, v[144:145]
	s_add_i32 m0, s36, 0x2000
	s_nop 0
	global_load_lds_dwordx4 v[186:187], off
	v_lshl_add_u64 v[186:187], v[246:247], 0, s[68:69]
	s_mov_b32 m0, s62
	s_nop 0
	global_load_lds_dwordx4 v[186:187], off
	v_lshl_add_u64 v[186:187], v[248:249], 0, s[68:69]
	s_mov_b32 m0, s63
	s_nop 0
	global_load_lds_dwordx4 v[186:187], off
	s_waitcnt vmcnt(8)
	s_waitcnt lgkmcnt(0)
	s_barrier
	s_setprio 1
	v_mfma_f32_16x16x32_bf16 v[62:65], v[160:163], v[212:215], v[62:65]
	v_mfma_f32_16x16x32_bf16 v[58:61], v[170:173], v[212:215], v[58:61]
	v_mfma_f32_16x16x32_bf16 v[46:49], v[160:163], v[220:223], v[46:49]
	v_mfma_f32_16x16x32_bf16 v[42:45], v[170:173], v[220:223], v[42:45]
	v_mfma_f32_16x16x32_bf16 v[30:33], v[160:163], v[228:231], v[30:33]
	v_mfma_f32_16x16x32_bf16 v[26:29], v[170:173], v[228:231], v[26:29]
	v_mfma_f32_16x16x32_bf16 v[14:17], v[160:163], v[236:239], v[14:17]
	v_mfma_f32_16x16x32_bf16 v[10:13], v[170:173], v[236:239], v[10:13]
	s_setprio 0
	s_setprio 1
	v_mfma_f32_16x16x32_bf16 v[62:65], v[164:167], v[216:219], v[62:65]
	v_mfma_f32_16x16x32_bf16 v[58:61], v[174:177], v[216:219], v[58:61]
	v_mfma_f32_16x16x32_bf16 v[46:49], v[164:167], v[224:227], v[46:49]
	v_mfma_f32_16x16x32_bf16 v[42:45], v[174:177], v[224:227], v[42:45]
	v_mfma_f32_16x16x32_bf16 v[30:33], v[164:167], v[232:235], v[30:33]
	v_mfma_f32_16x16x32_bf16 v[26:29], v[174:177], v[232:235], v[26:29]
	v_mfma_f32_16x16x32_bf16 v[14:17], v[164:167], v[240:243], v[14:17]
	v_mfma_f32_16x16x32_bf16 v[10:13], v[174:177], v[240:243], v[10:13]
	s_setprio 0
	s_setprio 1
	v_mfma_f32_16x16x32_bf16 v[54:57], v[178:181], v[212:215], v[54:57]
	v_mfma_f32_16x16x32_bf16 v[50:53], v[204:207], v[212:215], v[50:53]
	v_mfma_f32_16x16x32_bf16 v[38:41], v[178:181], v[220:223], v[38:41]
	v_mfma_f32_16x16x32_bf16 v[34:37], v[204:207], v[220:223], v[34:37]
	v_mfma_f32_16x16x32_bf16 v[22:25], v[178:181], v[228:231], v[22:25]
	v_mfma_f32_16x16x32_bf16 v[18:21], v[204:207], v[228:231], v[18:21]
	v_mfma_f32_16x16x32_bf16 v[6:9], v[178:181], v[236:239], v[6:9]
	v_mfma_f32_16x16x32_bf16 v[2:5], v[204:207], v[236:239], v[2:5]
	s_setprio 0
	s_setprio 1
	v_mfma_f32_16x16x32_bf16 v[54:57], v[182:185], v[216:219], v[54:57]
	v_mfma_f32_16x16x32_bf16 v[50:53], v[208:211], v[216:219], v[50:53]
	v_mfma_f32_16x16x32_bf16 v[38:41], v[182:185], v[224:227], v[38:41]
	v_mfma_f32_16x16x32_bf16 v[34:37], v[208:211], v[224:227], v[34:37]
	v_mfma_f32_16x16x32_bf16 v[22:25], v[182:185], v[232:235], v[22:25]
	v_mfma_f32_16x16x32_bf16 v[18:21], v[208:211], v[232:235], v[18:21]
	v_mfma_f32_16x16x32_bf16 v[6:9], v[182:185], v[240:243], v[6:9]
	v_mfma_f32_16x16x32_bf16 v[2:5], v[208:211], v[240:243], v[2:5]
	s_setprio 0
	s_barrier
	s_add_i32 s46, s46, 2
	s_add_u32 s60, s60, 0x100
	s_addc_u32 s73, s73, 0
	s_cmp_gt_u32 s46, 21
	s_mov_b64 s[36:37], s[42:43]
	s_cbranch_scc0 .LBB0_160
	s_and_b64 vcc, exec, s[10:11]
	s_cbranch_vccz .LBB0_163
	s_barrier

; #define PG8_STAGE(bufoff, gbase, voff) do { _Pragma("unroll") for (int _i = 0; _i < 2; ++_i) \
;         __builtin_amdgcn_global_load_lds((const unsigned*)((const char*)(gbase) + (voff)[_i]), (PG8_LAS unsigned*)(lds + (bufoff) + ldsw + _i * 8192), 16, 0, 0); } while (0)
; #define PG8_LDA(dst, b, h) do { _Pragma("unroll") for (int m = 0; m < 4; ++m) _Pragma("unroll") for (int k = 0; k < 2; ++k) dst[m][k] = *(const PG8_LAS bf16x8*)(lds + PG8_SA(b, h) + aoff + m * 2048 + k * 1024); } while (0)
; #define PG8_LDB(dst, b, h) do { _Pragma("unroll") for (int n = 0; n < 2; ++n) _Pragma("unroll") for (int k = 0; k < 2; ++k) dst[n][k] = *(const PG8_LAS bf16x8*)(lds + PG8_SB(b, h) + boff + n * 2048 + k * 1024); } while (0)
; #define PG8_WAIT_V(n) asm volatile("s_waitcnt vmcnt(" #n ")" ::: "memory")
; #define PG8_WAIT_L(n) asm volatile("s_waitcnt lgkmcnt(" #n ")" ::: "memory")
; #define PG8_BAR __builtin_amdgcn_s_barrier()
; #define PG8_SCHED __builtin_amdgcn_sched_barrier(0)
; template <class Epi, class Sched, bool ALIGN_EPI = false, bool SP2 = false>
; __device__ __forceinline__ void gemm_phase(PG8_LAS unsigned char* lds, const Gemm g, const Sched& S, const Epi& E) {
;     ...
;         const char* nA = has_next ? (const char*)g.A + (size_t)nxt.pm * tstep : cA; const char* nB = has_next ? (const char*)g.Bt + (size_t)nxt.pn * tstep : cB;
;         for (int t = 0; t < nt; t += 2) {
;             const bool last = (t == nt - 2);
;             const char* a1 = cA + (size_t)(t + 1) * kstep;
;             const char* a2 = last ? nA : cA + (size_t)(t + 2) * kstep; const char* b2 = last ? nB : cB + (size_t)(t + 2) * kstep;
;             const char* a3 = a2 + kstep; const char* b3 = b2 + kstep;
;             if (last && has_next) S.a_ready(nxt);
;             if constexpr (SP2) {
;             PG8_LDB(B0, 0, 0); PG8_LDB(B1, 0, 1); PG8_SCHED; PG8_LDA(At, 0, 0); PG8_STAGE(PG8_SA(1, 1), a1 + hstep, voffA);
;             PG8_WAIT_V(8); PG8_WAIT_L(0); PG8_BAR; PG8_MMA(0, 0, At, B0); PG8_MMA(0, 1, At, B1); PG8_BAR; PG8_SCHED;
;             PG8_LDA(At, 0, 1); PG8_STAGE(PG8_SB(0, 0), b2, voffB); PG8_STAGE(PG8_SB(0, 1), b2 + hstep, voffB); PG8_STAGE(PG8_SA(0, 0), a2, voffA);
;             PG8_WAIT_V(8); PG8_WAIT_L(0); PG8_BAR; PG8_MMA(1, 0, At, B0); PG8_MMA(1, 1, At, B1); PG8_BAR; PG8_SCHED;
.LBB0_281:
	s_add_u32 s18, s36, 0xfff80080
	s_addc_u32 s19, s37, -1
	s_add_i32 s73, 0, 0x10000
	s_cmp_eq_u32 s67, 28
	s_cselect_b32 s43, s9, s19
	s_cselect_b32 s42, s59, s18
	v_add_u32_e32 v163, s73, v160
	s_cselect_b32 s19, s7, s63
	s_cselect_b32 s18, s60, s62
	s_add_i32 s76, 0, 0x14000
	ds_read_b128 v[156:159], v163
	ds_read_b128 v[164:167], v163 offset:1024
	ds_read_b128 v[168:171], v163 offset:2048
	ds_read_b128 v[172:175], v163 offset:3072
	v_add_u32_e32 v163, s76, v160
	ds_read_b128 v[176:179], v163
	ds_read_b128 v[180:183], v163 offset:1024
	ds_read_b128 v[184:187], v163 offset:2048
	ds_read_b128 v[204:207], v163 offset:3072
	v_lshl_add_u64 v[240:241], s[36:37], 0, v[152:153]
	s_add_i32 m0, s30, 0xc000
	ds_read_b128 v[208:211], v162
	ds_read_b128 v[212:215], v162 offset:1024
	ds_read_b128 v[216:219], v162 offset:2048
	ds_read_b128 v[220:223], v162 offset:3072
	ds_read_b128 v[224:227], v162 offset:4096
	ds_read_b128 v[228:231], v162 offset:5120
	ds_read_b128 v[232:235], v162 offset:6144
	ds_read_b128 v[236:239], v162 offset:7168
	global_load_lds_dwordx4 v[240:241], off
	v_lshl_add_u64 v[240:241], s[36:37], 0, v[154:155]
	s_add_i32 m0, s30, 0xe000
	s_nop 0
	global_load_lds_dwordx4 v[240:241], off
	s_waitcnt vmcnt(8)
	s_waitcnt lgkmcnt(0)
	s_barrier
	s_setprio 1
	v_mfma_f32_16x16x32_bf16 v[126:129], v[156:159], v[208:211], v[126:129]
	v_mfma_f32_16x16x32_bf16 v[122:125], v[168:171], v[208:211], v[122:125]
	v_mfma_f32_16x16x32_bf16 v[110:113], v[156:159], v[216:219], v[110:113]
	v_mfma_f32_16x16x32_bf16 v[106:109], v[168:171], v[216:219], v[106:109]
	v_mfma_f32_16x16x32_bf16 v[94:97], v[156:159], v[224:227], v[94:97]
	v_mfma_f32_16x16x32_bf16 v[90:93], v[168:171], v[224:227], v[90:93]
	v_mfma_f32_16x16x32_bf16 v[78:81], v[156:159], v[232:235], v[78:81]
	v_mfma_f32_16x16x32_bf16 v[74:77], v[168:171], v[232:235], v[74:77]
	s_setprio 0
	s_setprio 1
	v_mfma_f32_16x16x32_bf16 v[126:129], v[164:167], v[212:215], v[126:129]
	v_mfma_f32_16x16x32_bf16 v[122:125], v[172:175], v[212:215], v[122:125]
	v_mfma_f32_16x16x32_bf16 v[110:113], v[164:167], v[220:223], v[110:113]
	v_mfma_f32_16x16x32_bf16 v[106:109], v[172:175], v[220:223], v[106:109]
	v_mfma_f32_16x16x32_bf16 v[94:97], v[164:167], v[228:231], v[94:97]
	v_mfma_f32_16x16x32_bf16 v[90:93], v[172:175], v[228:231], v[90:93]
	v_mfma_f32_16x16x32_bf16 v[78:81], v[164:167], v[236:239], v[78:81]
	v_mfma_f32_16x16x32_bf16 v[74:77], v[172:175], v[236:239], v[74:77]
	s_setprio 0
	s_setprio 1
	v_mfma_f32_16x16x32_bf16 v[118:121], v[176:179], v[208:211], v[118:121]
	v_mfma_f32_16x16x32_bf16 v[114:117], v[184:187], v[208:211], v[114:117]
	v_mfma_f32_16x16x32_bf16 v[102:105], v[176:179], v[216:219], v[102:105]
	v_mfma_f32_16x16x32_bf16 v[98:101], v[184:187], v[216:219], v[98:101]
	v_mfma_f32_16x16x32_bf16 v[86:89], v[176:179], v[224:227], v[86:89]
	v_mfma_f32_16x16x32_bf16 v[82:85], v[184:187], v[224:227], v[82:85]
	v_mfma_f32_16x16x32_bf16 v[70:73], v[176:179], v[232:235], v[70:73]
	v_mfma_f32_16x16x32_bf16 v[66:69], v[184:187], v[232:235], v[66:69]
	s_setprio 0
	s_setprio 1
	v_mfma_f32_16x16x32_bf16 v[118:121], v[180:183], v[212:215], v[118:121]
	v_mfma_f32_16x16x32_bf16 v[114:117], v[204:207], v[212:215], v[114:117]
	v_mfma_f32_16x16x32_bf16 v[102:105], v[180:183], v[220:223], v[102:105]
	v_mfma_f32_16x16x32_bf16 v[98:101], v[204:207], v[220:223], v[98:101]
	v_mfma_f32_16x16x32_bf16 v[86:89], v[180:183], v[228:231], v[86:89]
	v_mfma_f32_16x16x32_bf16 v[82:85], v[204:207], v[228:231], v[82:85]
	v_mfma_f32_16x16x32_bf16 v[70:73], v[180:183], v[236:239], v[70:73]
	v_mfma_f32_16x16x32_bf16 v[66:69], v[204:207], v[236:239], v[66:69]
	s_setprio 0
	s_barrier
	s_add_i32 s73, s73, s28
	v_lshl_add_u64 v[240:241], s[18:19], 0, v[146:147]
	s_mov_b32 m0, s73
	ds_read_b128 v[208:211], v162 offset:16384
	ds_read_b128 v[212:215], v162 offset:17408
	ds_read_b128 v[216:219], v162 offset:18432
	ds_read_b128 v[220:223], v162 offset:19456
	ds_read_b128 v[224:227], v162 offset:20480
	ds_read_b128 v[228:231], v162 offset:21504
	ds_read_b128 v[232:235], v162 offset:22528
	ds_read_b128 v[236:239], v162 offset:23552
	global_load_lds_dwordx4 v[240:241], off
	s_add_i32 m0, s73, 0x2000
	s_add_u32 s78, s18, 0x80000
	v_lshl_add_u64 v[242:243], s[18:19], 0, v[142:143]
	s_addc_u32 s79, s19, 0
	s_add_i32 s73, s76, s28
	global_load_lds_dwordx4 v[242:243], off
	v_lshl_add_u64 v[244:245], s[78:79], 0, v[146:147]
	s_mov_b32 m0, s73
	v_lshl_add_u64 v[246:247], s[42:43], 0, v[144:145]
	global_load_lds_dwordx4 v[244:245], off
	v_lshl_add_u64 v[244:245], s[78:79], 0, v[142:143]
	s_add_i32 m0, s73, 0x2000
	s_nop 0
	global_load_lds_dwordx4 v[244:245], off
	v_lshl_add_u64 v[244:245], s[42:43], 0, v[148:149]
	s_mov_b32 m0, s30
	s_nop 0
	global_load_lds_dwordx4 v[244:245], off
	s_mov_b32 m0, s34
	s_nop 0
	global_load_lds_dwordx4 v[246:247], off
	s_waitcnt vmcnt(8)
	s_waitcnt lgkmcnt(0)
	s_barrier
; #define PG8_STAGE(bufoff, gbase, voff) do { _Pragma("unroll") for (int _i = 0; _i < 2; ++_i) \
;         __builtin_amdgcn_global_load_lds((const unsigned*)((const char*)(gbase) + (voff)[_i]), (PG8_LAS unsigned*)(lds + (bufoff) + ldsw + _i * 8192), 16, 0, 0); } while (0)
; #define PG8_LDA(dst, b, h) do { _Pragma("unroll") for (int m = 0; m < 4; ++m) _Pragma("unroll") for (int k = 0; k < 2; ++k) dst[m][k] = *(const PG8_LAS bf16x8*)(lds + PG8_SA(b, h) + aoff + m * 2048 + k * 1024); } while (0)
; #define PG8_LDB(dst, b, h) do { _Pragma("unroll") for (int n = 0; n < 2; ++n) _Pragma("unroll") for (int k = 0; k < 2; ++k) dst[n][k] = *(const PG8_LAS bf16x8*)(lds + PG8_SB(b, h) + boff + n * 2048 + k * 1024); } while (0)
; #define PG8_MMA(ai, bj, At, Bt) do { __builtin_amdgcn_s_setprio(1); _Pragma("unroll") for (int m = 0; m < 4; ++m) _Pragma("unroll") for (int n = 0; n < 2; ++n) _Pragma("unroll") for (int k = 0; k < 2; ++k) \
;         acc[ai][bj][m][n] = __builtin_amdgcn_mfma_f32_16x16x32_bf16(Bt[n][k], At[m][k], acc[ai][bj][m][n], 0, 0, 0); __builtin_amdgcn_s_setprio(0); } while (0)
; #define PG8_WAIT_V(n) asm volatile("s_waitcnt vmcnt(" #n ")" ::: "memory")
; #define PG8_WAIT_L(n) asm volatile("s_waitcnt lgkmcnt(" #n ")" ::: "memory")
; #define PG8_BAR __builtin_amdgcn_s_barrier()
; #define PG8_SCHED __builtin_amdgcn_sched_barrier(0)
; template <class Epi, class Sched, bool ALIGN_EPI = false, bool SP2 = false>
; __device__ __forceinline__ void gemm_phase(PG8_LAS unsigned char* lds, const Gemm g, const Sched& S, const Epi& E) {
;     ...
;             PG8_WAIT_V(8); PG8_WAIT_L(0); PG8_BAR; PG8_MMA(1, 0, At, B0); PG8_MMA(1, 1, At, B1); PG8_BAR; PG8_SCHED;
;             PG8_LDB(B0, 1, 0); PG8_LDB(B1, 1, 1); PG8_SCHED; PG8_LDA(At, 1, 0); PG8_STAGE(PG8_SA(0, 1), a2 + hstep, voffA);
;             PG8_WAIT_V(8); PG8_WAIT_L(0); PG8_BAR; PG8_MMA(0, 0, At, B0); PG8_MMA(0, 1, At, B1); PG8_BAR; PG8_SCHED;
	s_setprio 1
	v_mfma_f32_16x16x32_bf16 v[62:65], v[156:159], v[208:211], v[62:65]
	v_mfma_f32_16x16x32_bf16 v[58:61], v[168:171], v[208:211], v[58:61]
	v_mfma_f32_16x16x32_bf16 v[46:49], v[156:159], v[216:219], v[46:49]
	v_mfma_f32_16x16x32_bf16 v[42:45], v[168:171], v[216:219], v[42:45]
	v_mfma_f32_16x16x32_bf16 v[30:33], v[156:159], v[224:227], v[30:33]
	v_mfma_f32_16x16x32_bf16 v[26:29], v[168:171], v[224:227], v[26:29]
	v_mfma_f32_16x16x32_bf16 v[14:17], v[156:159], v[232:235], v[14:17]
	v_mfma_f32_16x16x32_bf16 v[10:13], v[168:171], v[232:235], v[10:13]
	s_setprio 0
	s_setprio 1
	v_mfma_f32_16x16x32_bf16 v[62:65], v[164:167], v[212:215], v[62:65]
	v_mfma_f32_16x16x32_bf16 v[58:61], v[172:175], v[212:215], v[58:61]
	v_mfma_f32_16x16x32_bf16 v[46:49], v[164:167], v[220:223], v[46:49]
	v_mfma_f32_16x16x32_bf16 v[42:45], v[172:175], v[220:223], v[42:45]
	v_mfma_f32_16x16x32_bf16 v[30:33], v[164:167], v[228:231], v[30:33]
	v_mfma_f32_16x16x32_bf16 v[26:29], v[172:175], v[228:231], v[26:29]
	v_mfma_f32_16x16x32_bf16 v[14:17], v[164:167], v[236:239], v[14:17]
	v_mfma_f32_16x16x32_bf16 v[10:13], v[172:175], v[236:239], v[10:13]
	s_setprio 0
	s_setprio 1
	v_mfma_f32_16x16x32_bf16 v[54:57], v[176:179], v[208:211], v[54:57]
	v_mfma_f32_16x16x32_bf16 v[50:53], v[184:187], v[208:211], v[50:53]
	v_mfma_f32_16x16x32_bf16 v[38:41], v[176:179], v[216:219], v[38:41]
	v_mfma_f32_16x16x32_bf16 v[34:37], v[184:187], v[216:219], v[34:37]
	v_mfma_f32_16x16x32_bf16 v[22:25], v[176:179], v[224:227], v[22:25]
	v_mfma_f32_16x16x32_bf16 v[18:21], v[184:187], v[224:227], v[18:21]
	v_mfma_f32_16x16x32_bf16 v[6:9], v[176:179], v[232:235], v[6:9]
	v_mfma_f32_16x16x32_bf16 v[2:5], v[184:187], v[232:235], v[2:5]
	s_setprio 0
	s_setprio 1
	v_mfma_f32_16x16x32_bf16 v[54:57], v[180:183], v[212:215], v[54:57]
	v_mfma_f32_16x16x32_bf16 v[50:53], v[204:207], v[212:215], v[50:53]
	v_mfma_f32_16x16x32_bf16 v[38:41], v[180:183], v[220:223], v[38:41]
	v_mfma_f32_16x16x32_bf16 v[34:37], v[204:207], v[220:223], v[34:37]
	v_mfma_f32_16x16x32_bf16 v[22:25], v[180:183], v[228:231], v[22:25]
	v_mfma_f32_16x16x32_bf16 v[18:21], v[204:207], v[228:231], v[18:21]
	v_mfma_f32_16x16x32_bf16 v[6:9], v[180:183], v[236:239], v[6:9]
	v_mfma_f32_16x16x32_bf16 v[2:5], v[204:207], v[236:239], v[2:5]
	s_setprio 0
	s_barrier
	s_add_i32 s73, 0, 0x18000
	v_add_u32_e32 v163, s73, v160
	s_add_i32 s76, 0, 0x1c000
	ds_read_b128 v[156:159], v163
	ds_read_b128 v[164:167], v163 offset:1024
	ds_read_b128 v[168:171], v163 offset:2048
	ds_read_b128 v[172:175], v163 offset:3072
	v_add_u32_e32 v163, s76, v160
	ds_read_b128 v[176:179], v163
	ds_read_b128 v[180:183], v163 offset:1024
	ds_read_b128 v[184:187], v163 offset:2048
	ds_read_b128 v[204:207], v163 offset:3072
	s_add_u32 s42, s42, 0x80000
	s_addc_u32 s43, s43, 0
	s_mov_b32 m0, s44
	v_lshl_add_u64 v[248:249], s[42:43], 0, v[148:149]
	ds_read_b128 v[208:211], v162 offset:32768
	ds_read_b128 v[212:215], v162 offset:33792
	ds_read_b128 v[216:219], v162 offset:34816
	ds_read_b128 v[220:223], v162 offset:35840
	ds_read_b128 v[224:227], v162 offset:36864
	ds_read_b128 v[228:231], v162 offset:37888
	ds_read_b128 v[232:235], v162 offset:38912
	ds_read_b128 v[236:239], v162 offset:39936
	global_load_lds_dwordx4 v[248:249], off
	v_lshl_add_u64 v[248:249], s[42:43], 0, v[144:145]
	s_mov_b32 m0, s45
	s_nop 0
	global_load_lds_dwordx4 v[248:249], off
	s_waitcnt vmcnt(8)
	s_waitcnt lgkmcnt(0)
	s_barrier
	s_setprio 1
	v_mfma_f32_16x16x32_bf16 v[126:129], v[156:159], v[208:211], v[126:129]
	v_mfma_f32_16x16x32_bf16 v[122:125], v[168:171], v[208:211], v[122:125]
	v_mfma_f32_16x16x32_bf16 v[110:113], v[156:159], v[216:219], v[110:113]
	v_mfma_f32_16x16x32_bf16 v[106:109], v[168:171], v[216:219], v[106:109]
	v_mfma_f32_16x16x32_bf16 v[94:97], v[156:159], v[224:227], v[94:97]
	v_mfma_f32_16x16x32_bf16 v[90:93], v[168:171], v[224:227], v[90:93]
	v_mfma_f32_16x16x32_bf16 v[78:81], v[156:159], v[232:235], v[78:81]
	v_mfma_f32_16x16x32_bf16 v[74:77], v[168:171], v[232:235], v[74:77]
	s_setprio 0
	s_setprio 1
	v_mfma_f32_16x16x32_bf16 v[126:129], v[164:167], v[212:215], v[126:129]
	v_mfma_f32_16x16x32_bf16 v[122:125], v[172:175], v[212:215], v[122:125]
	v_mfma_f32_16x16x32_bf16 v[110:113], v[164:167], v[220:223], v[110:113]
	v_mfma_f32_16x16x32_bf16 v[106:109], v[172:175], v[220:223], v[106:109]
	v_mfma_f32_16x16x32_bf16 v[94:97], v[164:167], v[228:231], v[94:97]
	v_mfma_f32_16x16x32_bf16 v[90:93], v[172:175], v[228:231], v[90:93]
	v_mfma_f32_16x16x32_bf16 v[78:81], v[164:167], v[236:239], v[78:81]
	v_mfma_f32_16x16x32_bf16 v[74:77], v[172:175], v[236:239], v[74:77]
	s_setprio 0
	s_setprio 1
	v_mfma_f32_16x16x32_bf16 v[118:121], v[176:179], v[208:211], v[118:121]
	v_mfma_f32_16x16x32_bf16 v[114:117], v[184:187], v[208:211], v[114:117]
	v_mfma_f32_16x16x32_bf16 v[102:105], v[176:179], v[216:219], v[102:105]
	v_mfma_f32_16x16x32_bf16 v[98:101], v[184:187], v[216:219], v[98:101]
	v_mfma_f32_16x16x32_bf16 v[86:89], v[176:179], v[224:227], v[86:89]
	v_mfma_f32_16x16x32_bf16 v[82:85], v[184:187], v[224:227], v[82:85]
	v_mfma_f32_16x16x32_bf16 v[70:73], v[176:179], v[232:235], v[70:73]
	v_mfma_f32_16x16x32_bf16 v[66:69], v[184:187], v[232:235], v[66:69]
	s_setprio 0
	s_setprio 1
	v_mfma_f32_16x16x32_bf16 v[118:121], v[180:183], v[212:215], v[118:121]
	v_mfma_f32_16x16x32_bf16 v[114:117], v[204:207], v[212:215], v[114:117]
	v_mfma_f32_16x16x32_bf16 v[102:105], v[180:183], v[220:223], v[102:105]
	v_mfma_f32_16x16x32_bf16 v[98:101], v[204:207], v[220:223], v[98:101]
	v_mfma_f32_16x16x32_bf16 v[86:89], v[180:183], v[228:231], v[86:89]
	v_mfma_f32_16x16x32_bf16 v[82:85], v[204:207], v[228:231], v[82:85]
	v_mfma_f32_16x16x32_bf16 v[70:73], v[180:183], v[236:239], v[70:73]
	v_mfma_f32_16x16x32_bf16 v[66:69], v[204:207], v[236:239], v[66:69]
	s_setprio 0
	s_barrier
; #define PG8_STAGE(bufoff, gbase, voff) do { _Pragma("unroll") for (int _i = 0; _i < 2; ++_i) \
;         __builtin_amdgcn_global_load_lds((const unsigned*)((const char*)(gbase) + (voff)[_i]), (PG8_LAS unsigned*)(lds + (bufoff) + ldsw + _i * 8192), 16, 0, 0); } while (0)
; #define PG8_LDA(dst, b, h) do { _Pragma("unroll") for (int m = 0; m < 4; ++m) _Pragma("unroll") for (int k = 0; k < 2; ++k) dst[m][k] = *(const PG8_LAS bf16x8*)(lds + PG8_SA(b, h) + aoff + m * 2048 + k * 1024); } while (0)
; #define PG8_MMA(ai, bj, At, Bt) do { __builtin_amdgcn_s_setprio(1); _Pragma("unroll") for (int m = 0; m < 4; ++m) _Pragma("unroll") for (int n = 0; n < 2; ++n) _Pragma("unroll") for (int k = 0; k < 2; ++k) \
;         acc[ai][bj][m][n] = __builtin_amdgcn_mfma_f32_16x16x32_bf16(Bt[n][k], At[m][k], acc[ai][bj][m][n], 0, 0, 0); __builtin_amdgcn_s_setprio(0); } while (0)
; #define PG8_WAIT_V(n) asm volatile("s_waitcnt vmcnt(" #n ")" ::: "memory")
; #define PG8_WAIT_L(n) asm volatile("s_waitcnt lgkmcnt(" #n ")" ::: "memory")
; #define PG8_BAR __builtin_amdgcn_s_barrier()
; #define PG8_SCHED __builtin_amdgcn_sched_barrier(0)
;     __device__ __forceinline__ void operator()(const f32x4 (&acc)[2][2][4][2], const Unit& u, int wr, int wc, int fr, int fq) const {
;     ...
;         if (u.pn >= 30) {
; template <class Epi, class Sched, bool ALIGN_EPI = false, bool SP2 = false>
; __device__ __forceinline__ void gemm_phase(PG8_LAS unsigned char* lds, const Gemm g, const Sched& S, const Epi& E) {
;     ...
;             PG8_LDA(At, 1, 1); PG8_STAGE(PG8_SB(1, 0), b3, voffB); PG8_STAGE(PG8_SB(1, 1), b3 + hstep, voffB); PG8_STAGE(PG8_SA(1, 0), a3, voffA);
;             PG8_WAIT_V(8); PG8_WAIT_L(0); PG8_BAR; PG8_MMA(1, 0, At, B0); PG8_MMA(1, 1, At, B1); PG8_BAR; PG8_SCHED;
	s_add_i32 s42, s73, s28
	v_lshl_add_u64 v[240:241], v[240:241], 0, s[68:69]
	s_mov_b32 m0, s42
	ds_read_b128 v[208:211], v162 offset:49152
	ds_read_b128 v[212:215], v162 offset:50176
	ds_read_b128 v[216:219], v162 offset:51200
	ds_read_b128 v[220:223], v162 offset:52224
	ds_read_b128 v[224:227], v162 offset:53248
	ds_read_b128 v[228:231], v162 offset:54272
	ds_read_b128 v[232:235], v162 offset:55296
	ds_read_b128 v[236:239], v162 offset:56320
	global_load_lds_dwordx4 v[240:241], off
	s_add_i32 m0, s42, 0x2000
	s_add_u32 s18, s18, 0x80080
	v_lshl_add_u64 v[240:241], v[242:243], 0, s[68:69]
	s_addc_u32 s19, s19, 0
	s_add_i32 s42, s76, s28
	global_load_lds_dwordx4 v[240:241], off
	v_lshl_add_u64 v[240:241], s[18:19], 0, v[146:147]
	s_mov_b32 m0, s42
	s_nop 0
	global_load_lds_dwordx4 v[240:241], off
	v_lshl_add_u64 v[240:241], s[18:19], 0, v[142:143]
	s_add_i32 m0, s42, 0x2000
	s_nop 0
	global_load_lds_dwordx4 v[240:241], off
	v_lshl_add_u64 v[240:241], v[244:245], 0, s[68:69]
	s_mov_b32 m0, s46
	s_nop 0
	global_load_lds_dwordx4 v[240:241], off
	v_lshl_add_u64 v[240:241], v[246:247], 0, s[68:69]
	s_mov_b32 m0, s47
	s_nop 0
	global_load_lds_dwordx4 v[240:241], off
	s_waitcnt vmcnt(8)
	s_waitcnt lgkmcnt(0)
	s_barrier
	s_setprio 1
	v_mfma_f32_16x16x32_bf16 v[62:65], v[156:159], v[208:211], v[62:65]
	v_mfma_f32_16x16x32_bf16 v[58:61], v[168:171], v[208:211], v[58:61]
	v_mfma_f32_16x16x32_bf16 v[46:49], v[156:159], v[216:219], v[46:49]
	v_mfma_f32_16x16x32_bf16 v[42:45], v[168:171], v[216:219], v[42:45]
	v_mfma_f32_16x16x32_bf16 v[30:33], v[156:159], v[224:227], v[30:33]
	v_mfma_f32_16x16x32_bf16 v[26:29], v[168:171], v[224:227], v[26:29]
	v_mfma_f32_16x16x32_bf16 v[14:17], v[156:159], v[232:235], v[14:17]
	v_mfma_f32_16x16x32_bf16 v[10:13], v[168:171], v[232:235], v[10:13]
	s_setprio 0
	s_setprio 1
	v_mfma_f32_16x16x32_bf16 v[62:65], v[164:167], v[212:215], v[62:65]
	v_mfma_f32_16x16x32_bf16 v[58:61], v[172:175], v[212:215], v[58:61]
	v_mfma_f32_16x16x32_bf16 v[46:49], v[164:167], v[220:223], v[46:49]
	v_mfma_f32_16x16x32_bf16 v[42:45], v[172:175], v[220:223], v[42:45]
	v_mfma_f32_16x16x32_bf16 v[30:33], v[164:167], v[228:231], v[30:33]
	v_mfma_f32_16x16x32_bf16 v[26:29], v[172:175], v[228:231], v[26:29]
	v_mfma_f32_16x16x32_bf16 v[14:17], v[164:167], v[236:239], v[14:17]
	v_mfma_f32_16x16x32_bf16 v[10:13], v[172:175], v[236:239], v[10:13]
	s_setprio 0
	s_setprio 1
	v_mfma_f32_16x16x32_bf16 v[54:57], v[176:179], v[208:211], v[54:57]
	v_mfma_f32_16x16x32_bf16 v[50:53], v[184:187], v[208:211], v[50:53]
	v_mfma_f32_16x16x32_bf16 v[38:41], v[176:179], v[216:219], v[38:41]
	v_mfma_f32_16x16x32_bf16 v[34:37], v[184:187], v[216:219], v[34:37]
	v_mfma_f32_16x16x32_bf16 v[22:25], v[176:179], v[224:227], v[22:25]
	v_mfma_f32_16x16x32_bf16 v[18:21], v[184:187], v[224:227], v[18:21]
	v_mfma_f32_16x16x32_bf16 v[6:9], v[176:179], v[232:235], v[6:9]
	v_mfma_f32_16x16x32_bf16 v[2:5], v[184:187], v[232:235], v[2:5]
	s_setprio 0
	s_setprio 1
	v_mfma_f32_16x16x32_bf16 v[54:57], v[180:183], v[212:215], v[54:57]
	v_mfma_f32_16x16x32_bf16 v[50:53], v[204:207], v[212:215], v[50:53]
	v_mfma_f32_16x16x32_bf16 v[38:41], v[180:183], v[220:223], v[38:41]
	v_mfma_f32_16x16x32_bf16 v[34:37], v[204:207], v[220:223], v[34:37]
	v_mfma_f32_16x16x32_bf16 v[22:25], v[180:183], v[228:231], v[22:25]
	v_mfma_f32_16x16x32_bf16 v[18:21], v[204:207], v[228:231], v[18:21]
	v_mfma_f32_16x16x32_bf16 v[6:9], v[180:183], v[236:239], v[6:9]
	v_mfma_f32_16x16x32_bf16 v[2:5], v[204:207], v[236:239], v[2:5]
	s_setprio 0
	s_barrier
	s_add_i32 s67, s67, 2
	s_add_u32 s36, s36, 0x100
	s_addc_u32 s37, s37, 0
	s_add_u32 s62, s62, 0x100
	s_addc_u32 s63, s63, 0
	s_cmp_gt_u32 s67, 29
	s_cbranch_scc0 .LBB0_281
	s_and_b64 vcc, exec, s[4:5]
	s_cbranch_vccnz .LBB0_286
	s_cmp_lt_i32 s57, 30
	s_mov_b64 s[18:19], -1
	s_cbranch_scc1 .LBB0_287
